# FF2 K-loop: loader-wave LDS-DMA issue + 16x16x32 bf16 MFMA; P3a final epilogue via f32 LDS staging with batched gate loads
# speedup vs baseline: 1.1499x; 1.0146x over previous
; template <class AL, class BL>
; DEV void gemm_ktile(Acc& acc, const char* A, const char* B, int wm, int wn, int lr, int lh, const AL& al, const BL& bl,
;                     int tid, int m0, int n0, int knext, char* nxt, R4& ra, R4& rb) {
;     ...
;   for (int ks = 0; ks < 4; ++ks) {
;     const int cur = ks & 1, nx = cur ^ 1;
;     if (ks < 3) {
; #pragma unroll
;       for (int i = 0; i < 4; ++i) a[nx][i] = *(const bf16x8*)(pa + 32 * i * LDSROW + (ks + 1) * 32);
; #pragma unroll
;       for (int j = 0; j < 2; ++j) b[nx][j] = *(const bf16x8*)(pb + 32 * j * LDSROW + (ks + 1) * 32);
;     }
;     __builtin_amdgcn_sched_barrier(0);
; #pragma unroll
;     for (int i = 0; i < 4; ++i)
; #pragma unroll
;       for (int j = 0; j < 2; ++j)
;         acc[i][j] = __builtin_amdgcn_mfma_f32_32x32x16_bf16(a[cur][i], b[cur][j], acc[i][j], 0, 0, 0);
;     __builtin_amdgcn_sched_barrier(0);
;     if (ks == 1) {
;       al.store(tid, nxt, ra);
;       bl.store(tid, nxt + TILE_BYTES, rb);
;       __builtin_amdgcn_sched_barrier(0);
;       ra = al.load(tid, m0, knext);
;       rb = bl.load(tid, n0, knext);
;       __builtin_amdgcn_sched_barrier(0);
;     }
;   }
.LBB0_940:
	s_add_i32 s5, s0, -2
	s_and_b32 s5, s5, 2
	s_mul_i32 s6, s5, 0x9000
	s_add_i32 s5, s1, 1
	s_and_b32 s7, s0, 2
	s_min_u32 s1, s1, 5
	s_mul_i32 s7, s7, 0x9000
	v_add3_u32 v173, s6, v164, v171
	v_add3_u32 v217, s6, v172, v171
	ds_read_b128 v[174:177], v173
	ds_read_b128 v[178:181], v173 offset:32
	ds_read_b128 v[182:185], v173 offset:4608
	ds_read_b128 v[186:189], v173 offset:4640
	ds_read_b128 v[190:193], v173 offset:9216
	ds_read_b128 v[194:197], v173 offset:9248
	ds_read_b128 v[198:201], v173 offset:13824
	ds_read_b128 v[222:225], v173 offset:13856
	ds_read_b128 v[226:229], v217 offset:36864
	ds_read_b128 v[230:233], v217 offset:36896
	ds_read_b128 v[234:237], v217 offset:41472
	ds_read_b128 v[238:241], v217 offset:41504
	v_add_u32_e32 v242, s7, v170
	s_waitcnt lgkmcnt(3)
	v_mfma_f32_32x32x16_bf16 v[0:15], v[174:177], v[226:229], v[0:15]
	s_waitcnt lgkmcnt(1)
	v_mfma_f32_32x32x16_bf16 v[32:47], v[174:177], v[234:237], v[32:47]
	v_mfma_f32_32x32x16_bf16 v[16:31], v[182:185], v[226:229], v[16:31]
	v_mfma_f32_32x32x16_bf16 v[80:95], v[182:185], v[234:237], v[80:95]
	v_mfma_f32_32x32x16_bf16 v[48:63], v[190:193], v[226:229], v[48:63]
	v_mfma_f32_32x32x16_bf16 v[112:127], v[190:193], v[234:237], v[112:127]
	v_mfma_f32_32x32x16_bf16 v[96:111], v[198:201], v[226:229], v[96:111]
	v_mfma_f32_32x32x16_bf16 v[64:79], v[198:201], v[234:237], v[64:79]
	ds_read_b128 v[174:177], v173 offset:64
	ds_read_b128 v[182:185], v173 offset:4672
	ds_read_b128 v[190:193], v173 offset:9280
	ds_read_b128 v[198:201], v173 offset:13888
	ds_read_b128 v[226:229], v217 offset:36928
	ds_read_b128 v[234:237], v217 offset:41536
	v_mfma_f32_32x32x16_bf16 v[0:15], v[178:181], v[230:233], v[0:15]
	s_waitcnt lgkmcnt(6)
	v_mfma_f32_32x32x16_bf16 v[32:47], v[178:181], v[238:241], v[32:47]
	v_mfma_f32_32x32x16_bf16 v[16:31], v[186:189], v[230:233], v[16:31]
	v_mfma_f32_32x32x16_bf16 v[80:95], v[186:189], v[238:241], v[80:95]
	v_mfma_f32_32x32x16_bf16 v[48:63], v[194:197], v[230:233], v[48:63]
	v_mfma_f32_32x32x16_bf16 v[112:127], v[194:197], v[238:241], v[112:127]
	v_mfma_f32_32x32x16_bf16 v[96:111], v[222:225], v[230:233], v[96:111]
	v_mfma_f32_32x32x16_bf16 v[64:79], v[222:225], v[238:241], v[64:79]
	s_lshl_b32 s84, s1, 7
	v_lshl_add_u64 v[160:161], v[166:167], 0, s[84:85]
	s_waitcnt vmcnt(5)
	ds_write_b128 v242, v[136:139]
	ds_write_b128 v242, v[128:131] offset:9216
	ds_write_b128 v242, v[132:135] offset:18432
	s_waitcnt vmcnt(3)
	ds_write_b128 v242, v[148:151] offset:27648
	v_lshl_add_u64 v[178:179], v[168:169], 0, s[84:85]
	ds_write_b128 v242, v[140:143] offset:36864
	s_waitcnt vmcnt(2)
	ds_write_b128 v242, v[144:147] offset:46080
	s_waitcnt vmcnt(1)
	ds_write_b128 v242, v[152:155] offset:55296
	s_waitcnt vmcnt(0)
	ds_write_b128 v242, v[156:159] offset:64512
	v_add_co_u32_e32 v128, vcc, s11, v160
	s_nop 1
	v_addc_co_u32_e32 v129, vcc, 0, v161, vcc
	v_add_co_u32_e32 v132, vcc, s12, v160
	s_nop 1
	v_addc_co_u32_e32 v133, vcc, 0, v161, vcc
	v_add_co_u32_e32 v144, vcc, s13, v160
	global_load_dwordx4 v[128:131], v[128:129], off offset:1280
	s_nop 0
	global_load_dwordx4 v[132:135], v[132:133], off offset:1280
	v_addc_co_u32_e32 v145, vcc, 0, v161, vcc
	v_add_co_u32_e32 v146, vcc, s8, v178
	global_load_dwordx4 v[136:139], v[160:161], off offset:1280
	global_load_dwordx4 v[140:143], v[178:179], off offset:1280
	v_addc_co_u32_e32 v147, vcc, 0, v179, vcc
	v_add_co_u32_e32 v152, vcc, s9, v178
	global_load_dwordx4 v[148:151], v[144:145], off offset:1280
	s_nop 0
	global_load_dwordx4 v[144:147], v[146:147], off offset:1280
	v_addc_co_u32_e32 v153, vcc, 0, v179, vcc
	v_add_co_u32_e32 v156, vcc, s10, v178
	s_nop 1
	v_addc_co_u32_e32 v157, vcc, 0, v179, vcc
	global_load_dwordx4 v[152:155], v[152:153], off offset:1280
	s_nop 0
	global_load_dwordx4 v[156:159], v[156:157], off offset:1280
	ds_read_b128 v[178:181], v173 offset:96
	ds_read_b128 v[186:189], v173 offset:4704
	ds_read_b128 v[194:197], v173 offset:9312
	ds_read_b128 v[222:225], v173 offset:13920
	ds_read_b128 v[230:233], v217 offset:36960
	ds_read_b128 v[238:241], v217 offset:41568
	s_waitcnt lgkmcnt(14)
	v_mfma_f32_32x32x16_bf16 v[0:15], v[174:177], v[226:229], v[0:15]
	v_mfma_f32_32x32x16_bf16 v[32:47], v[174:177], v[234:237], v[32:47]
	v_mfma_f32_32x32x16_bf16 v[16:31], v[182:185], v[226:229], v[16:31]
	v_mfma_f32_32x32x16_bf16 v[80:95], v[182:185], v[234:237], v[80:95]
	v_mfma_f32_32x32x16_bf16 v[48:63], v[190:193], v[226:229], v[48:63]
	v_mfma_f32_32x32x16_bf16 v[112:127], v[190:193], v[234:237], v[112:127]
	v_mfma_f32_32x32x16_bf16 v[96:111], v[198:201], v[226:229], v[96:111]
	v_mfma_f32_32x32x16_bf16 v[64:79], v[198:201], v[234:237], v[64:79]
	s_waitcnt lgkmcnt(1)
	v_mfma_f32_32x32x16_bf16 v[0:15], v[178:181], v[230:233], v[0:15]
	s_waitcnt lgkmcnt(0)
	v_mfma_f32_32x32x16_bf16 v[32:47], v[178:181], v[238:241], v[32:47]
	v_mfma_f32_32x32x16_bf16 v[16:31], v[186:189], v[230:233], v[16:31]
	v_mfma_f32_32x32x16_bf16 v[80:95], v[186:189], v[238:241], v[80:95]
	v_mfma_f32_32x32x16_bf16 v[48:63], v[194:197], v[230:233], v[48:63]
	v_mfma_f32_32x32x16_bf16 v[112:127], v[194:197], v[238:241], v[112:127]
	v_mfma_f32_32x32x16_bf16 v[96:111], v[222:225], v[230:233], v[96:111]
	v_mfma_f32_32x32x16_bf16 v[64:79], v[222:225], v[238:241], v[64:79]
	s_add_i32 s0, s0, 2
	s_cmp_lg_u32 s5, 8
	s_mov_b32 s1, s5
	s_barrier
	s_cbranch_scc1 .LBB0_940
; DEV u16 f2bf(float f) { return (u16)(pack2(f, f) & 0xffffu); }
; DEV float bf2f(u16 h) { return __uint_as_float(((unsigned)h) << 16); }
; template <class F>
; DEV void acc_foreach(Acc& acc, int m0, int n0, F f) {
;   asm volatile("s_nop 7\n\ts_nop 7\n\ts_nop 3" ::: "memory");
;   const int tid = tidx_full();
;   const int wave = tid >> 6, lane = tid & 63;
;   const int wm = (wave >> 2) * 128, wn = (wave & 3) * 64;
;   const int lr = lane & 31, lh = lane >> 5;
; #pragma unroll
;   for (int i = 0; i < 4; ++i)
; #pragma unroll
;     for (int j = 0; j < 2; ++j)
; #pragma unroll
;       for (int r = 0; r < 16; ++r) {
;         const int m = m0 + wm + 32 * i + (r & 3) + 8 * (r >> 2) + 4 * lh;
;         const int n = n0 + wn + 32 * j + lr;
;         float v = acc[i][j][r];
;         f(m, n, v);
;         acc[i][j][r] = v;
;       }
; DEV void phase_p3a(const Params& p, int g, char* smem) {
;     ...
;     acc_foreach(acc, m0, n0, [&](int m, int n, float& v) {
;       const float gb = bf2f(GT[(size_t)m * 2048 + 1024 + n]);
;       PHG[(size_t)m * 2560 + 1024 + n] = f2bf(gb * v);
;     });
	s_add_i32 s4, s4, 1
	s_waitcnt vmcnt(0)
	s_nop 7
	s_nop 7
	s_nop 3
	v_and_b32_e32 v160, 63, v202
	v_lshrrev_b32_e32 v161, 6, v202
	v_mul_u32_u24_e32 v164, 0x2400, v161
	v_add_u32_e32 v164, 0x12000, v164
	v_and_b32_e32 v230, 31, v160
	v_lshrrev_b32_e32 v231, 5, v160
	v_lshlrev_b32_e32 v230, 2, v230
	v_lshl_add_u32 v230, v231, 10, v230
	v_add_u32_e32 v222, v164, v230
	v_lshrrev_b32_e32 v230, 4, v160
	v_and_b32_e32 v231, 15, v160
	v_lshlrev_b32_e32 v226, 4, v231
	v_lshl_add_u32 v226, v230, 8, v226
	v_add_u32_e32 v223, v164, v226
	v_lshrrev_b32_e32 v226, 2, v161
	v_lshl_add_u32 v226, v226, 7, v230
	v_add_u32_e32 v226, s3, v226
	v_and_b32_e32 v227, 3, v161
	v_lshl_add_u32 v227, v227, 4, v231
	v_lshlrev_b32_e32 v227, 3, v227
	s_lshl_b32 s100, s2, 1
	s_add_u32 s100, s100, 0x800
	v_add_u32_e32 v227, s100, v227
	v_lshl_add_u32 v224, v226, 12, v227
	v_mul_u32_u24_e32 v225, 0x1400, v226
	v_add_u32_e32 v225, v225, v227
	v_readlane_b32 s2, v249, 48
	v_readlane_b32 s3, v249, 49
	s_nop 4
	global_load_dwordx2 v[128:129], v224, s[2:3]
	v_add_u32_e32 v224, 0x4000, v224
	global_load_dwordx2 v[130:131], v224, s[2:3]
	v_add_u32_e32 v224, 0x4000, v224
	global_load_dwordx2 v[132:133], v224, s[2:3]
	v_add_u32_e32 v224, 0x4000, v224
	global_load_dwordx2 v[134:135], v224, s[2:3]
	v_add_u32_e32 v224, 0x4000, v224
	global_load_dwordx2 v[136:137], v224, s[2:3]
	v_add_u32_e32 v224, 0x4000, v224
	global_load_dwordx2 v[138:139], v224, s[2:3]
	v_add_u32_e32 v224, 0x4000, v224
	global_load_dwordx2 v[140:141], v224, s[2:3]
	v_add_u32_e32 v224, 0x4000, v224
	global_load_dwordx2 v[142:143], v224, s[2:3]
	v_add_u32_e32 v224, 0x4000, v224
	global_load_dwordx2 v[144:145], v224, s[2:3]
	v_add_u32_e32 v224, 0x4000, v224
	global_load_dwordx2 v[146:147], v224, s[2:3]
	v_add_u32_e32 v224, 0x4000, v224
	global_load_dwordx2 v[148:149], v224, s[2:3]
	v_add_u32_e32 v224, 0x4000, v224
	global_load_dwordx2 v[150:151], v224, s[2:3]
	v_add_u32_e32 v224, 0x4000, v224
	global_load_dwordx2 v[152:153], v224, s[2:3]
	v_add_u32_e32 v224, 0x4000, v224
	global_load_dwordx2 v[154:155], v224, s[2:3]
	v_add_u32_e32 v224, 0x4000, v224
	global_load_dwordx2 v[156:157], v224, s[2:3]
	v_add_u32_e32 v224, 0x4000, v224
	global_load_dwordx2 v[158:159], v224, s[2:3]
	v_add_u32_e32 v224, 0x4000, v224
	global_load_dwordx2 v[170:171], v224, s[2:3]
	v_add_u32_e32 v224, 0x4000, v224
	global_load_dwordx2 v[172:173], v224, s[2:3]
	v_add_u32_e32 v224, 0x4000, v224
	global_load_dwordx2 v[174:175], v224, s[2:3]
	v_add_u32_e32 v224, 0x4000, v224
	global_load_dwordx2 v[176:177], v224, s[2:3]
	v_add_u32_e32 v224, 0x4000, v224
	global_load_dwordx2 v[178:179], v224, s[2:3]
	v_add_u32_e32 v224, 0x4000, v224
	global_load_dwordx2 v[180:181], v224, s[2:3]
	v_add_u32_e32 v224, 0x4000, v224
	global_load_dwordx2 v[182:183], v224, s[2:3]
	v_add_u32_e32 v224, 0x4000, v224
	global_load_dwordx2 v[184:185], v224, s[2:3]
	v_add_u32_e32 v224, 0x4000, v224
	global_load_dwordx2 v[186:187], v224, s[2:3]
	v_add_u32_e32 v224, 0x4000, v224
	global_load_dwordx2 v[188:189], v224, s[2:3]
	v_add_u32_e32 v224, 0x4000, v224
	global_load_dwordx2 v[190:191], v224, s[2:3]
	v_add_u32_e32 v224, 0x4000, v224
	global_load_dwordx2 v[192:193], v224, s[2:3]
	v_add_u32_e32 v224, 0x4000, v224
	global_load_dwordx2 v[194:195], v224, s[2:3]
	v_add_u32_e32 v224, 0x4000, v224
	global_load_dwordx2 v[196:197], v224, s[2:3]
	v_add_u32_e32 v224, 0x4000, v224
	global_load_dwordx2 v[198:199], v224, s[2:3]
	v_add_u32_e32 v224, 0x4000, v224
	global_load_dwordx2 v[200:201], v224, s[2:3]
	v_add_u32_e32 v224, 0x4000, v224
	ds_write_b32 v222, v0
	ds_write_b32 v222, v1 offset:256
	ds_write_b32 v222, v2 offset:512
	ds_write_b32 v222, v3 offset:768
	ds_write_b32 v222, v4 offset:2048
	ds_write_b32 v222, v5 offset:2304
	ds_write_b32 v222, v6 offset:2560
	ds_write_b32 v222, v7 offset:2816
	ds_write_b32 v222, v8 offset:4096
	ds_write_b32 v222, v9 offset:4352
	ds_write_b32 v222, v10 offset:4608
	ds_write_b32 v222, v11 offset:4864
	ds_write_b32 v222, v12 offset:6144
	ds_write_b32 v222, v13 offset:6400
	ds_write_b32 v222, v14 offset:6656
	ds_write_b32 v222, v15 offset:6912
	ds_write_b32 v222, v32 offset:128
	ds_write_b32 v222, v33 offset:384
	ds_write_b32 v222, v34 offset:640
	ds_write_b32 v222, v35 offset:896
	ds_write_b32 v222, v36 offset:2176
	ds_write_b32 v222, v37 offset:2432
	ds_write_b32 v222, v38 offset:2688
	ds_write_b32 v222, v39 offset:2944
	ds_write_b32 v222, v40 offset:4224
	ds_write_b32 v222, v41 offset:4480
	ds_write_b32 v222, v42 offset:4736
	ds_write_b32 v222, v43 offset:4992
	ds_write_b32 v222, v44 offset:6272
	ds_write_b32 v222, v45 offset:6528
	ds_write_b32 v222, v46 offset:6784
	ds_write_b32 v222, v47 offset:7040
	s_waitcnt lgkmcnt(0)
	ds_read_b128 v[0:3], v223
	ds_read_b128 v[4:7], v223 offset:1024
	ds_read_b128 v[8:11], v223 offset:2048
	ds_read_b128 v[12:15], v223 offset:3072
	ds_read_b128 v[32:35], v223 offset:4096
	ds_read_b128 v[36:39], v223 offset:5120
	ds_read_b128 v[40:43], v223 offset:6144
	ds_read_b128 v[44:47], v223 offset:7168
	s_waitcnt vmcnt(31) lgkmcnt(7)
	v_lshlrev_b32_e32 v226, 16, v128
	v_and_b32_e32 v227, 0xffff0000, v128
	v_lshlrev_b32_e32 v228, 16, v129
	v_and_b32_e32 v229, 0xffff0000, v129
	v_mul_f32_e32 v0, v226, v0
	v_mul_f32_e32 v1, v227, v1
	v_mul_f32_e32 v2, v228, v2
	v_mul_f32_e32 v3, v229, v3
	v_cvt_pk_bf16_f32 v0, v0, v1
	v_cvt_pk_bf16_f32 v1, v2, v3
	global_store_dwordx2 v225, v[0:1], s[56:57]
	v_add_u32_e32 v225, 0x5000, v225
	s_waitcnt vmcnt(31) lgkmcnt(6)
; DEV u16 f2bf(float f) { return (u16)(pack2(f, f) & 0xffffu); }
; DEV float bf2f(u16 h) { return __uint_as_float(((unsigned)h) << 16); }
; DEV void phase_p3a(const Params& p, int g, char* smem) {
;     ...
;     acc_foreach(acc, m0, n0, [&](int m, int n, float& v) {
;       const float gb = bf2f(GT[(size_t)m * 2048 + 1024 + n]);
;       PHG[(size_t)m * 2560 + 1024 + n] = f2bf(gb * v);
;     });
	v_lshlrev_b32_e32 v226, 16, v130
	v_and_b32_e32 v227, 0xffff0000, v130
	v_lshlrev_b32_e32 v228, 16, v131
	v_and_b32_e32 v229, 0xffff0000, v131
	v_mul_f32_e32 v4, v226, v4
	v_mul_f32_e32 v5, v227, v5
	v_mul_f32_e32 v6, v228, v6
	v_mul_f32_e32 v7, v229, v7
	v_cvt_pk_bf16_f32 v4, v4, v5
	v_cvt_pk_bf16_f32 v5, v6, v7
	global_store_dwordx2 v225, v[4:5], s[56:57]
	v_add_u32_e32 v225, 0x5000, v225
	s_waitcnt vmcnt(31) lgkmcnt(5)
	v_lshlrev_b32_e32 v226, 16, v132
	v_and_b32_e32 v227, 0xffff0000, v132
	v_lshlrev_b32_e32 v228, 16, v133
	v_and_b32_e32 v229, 0xffff0000, v133
	v_mul_f32_e32 v8, v226, v8
	v_mul_f32_e32 v9, v227, v9
	v_mul_f32_e32 v10, v228, v10
	v_mul_f32_e32 v11, v229, v11
	v_cvt_pk_bf16_f32 v8, v8, v9
	v_cvt_pk_bf16_f32 v9, v10, v11
	global_store_dwordx2 v225, v[8:9], s[56:57]
	v_add_u32_e32 v225, 0x5000, v225
	s_waitcnt vmcnt(31) lgkmcnt(4)
	v_lshlrev_b32_e32 v226, 16, v134
	v_and_b32_e32 v227, 0xffff0000, v134
	v_lshlrev_b32_e32 v228, 16, v135
	v_and_b32_e32 v229, 0xffff0000, v135
	v_mul_f32_e32 v12, v226, v12
	v_mul_f32_e32 v13, v227, v13
	v_mul_f32_e32 v14, v228, v14
	v_mul_f32_e32 v15, v229, v15
	v_cvt_pk_bf16_f32 v12, v12, v13
	v_cvt_pk_bf16_f32 v13, v14, v15
	global_store_dwordx2 v225, v[12:13], s[56:57]
	v_add_u32_e32 v225, 0x5000, v225
	s_waitcnt vmcnt(31) lgkmcnt(3)
	v_lshlrev_b32_e32 v226, 16, v136
	v_and_b32_e32 v227, 0xffff0000, v136
	v_lshlrev_b32_e32 v228, 16, v137
	v_and_b32_e32 v229, 0xffff0000, v137
	v_mul_f32_e32 v32, v226, v32
	v_mul_f32_e32 v33, v227, v33
	v_mul_f32_e32 v34, v228, v34
	v_mul_f32_e32 v35, v229, v35
	v_cvt_pk_bf16_f32 v32, v32, v33
	v_cvt_pk_bf16_f32 v33, v34, v35
	global_store_dwordx2 v225, v[32:33], s[56:57]
	v_add_u32_e32 v225, 0x5000, v225
	s_waitcnt vmcnt(31) lgkmcnt(2)
	v_lshlrev_b32_e32 v226, 16, v138
	v_and_b32_e32 v227, 0xffff0000, v138
	v_lshlrev_b32_e32 v228, 16, v139
	v_and_b32_e32 v229, 0xffff0000, v139
	v_mul_f32_e32 v36, v226, v36
	v_mul_f32_e32 v37, v227, v37
	v_mul_f32_e32 v38, v228, v38
	v_mul_f32_e32 v39, v229, v39
	v_cvt_pk_bf16_f32 v36, v36, v37
	v_cvt_pk_bf16_f32 v37, v38, v39
	global_store_dwordx2 v225, v[36:37], s[56:57]
	v_add_u32_e32 v225, 0x5000, v225
	s_waitcnt vmcnt(31) lgkmcnt(1)
	v_lshlrev_b32_e32 v226, 16, v140
	v_and_b32_e32 v227, 0xffff0000, v140
	v_lshlrev_b32_e32 v228, 16, v141
	v_and_b32_e32 v229, 0xffff0000, v141
	v_mul_f32_e32 v40, v226, v40
	v_mul_f32_e32 v41, v227, v41
	v_mul_f32_e32 v42, v228, v42
	v_mul_f32_e32 v43, v229, v43
	v_cvt_pk_bf16_f32 v40, v40, v41
	v_cvt_pk_bf16_f32 v41, v42, v43
	global_store_dwordx2 v225, v[40:41], s[56:57]
	v_add_u32_e32 v225, 0x5000, v225
	s_waitcnt vmcnt(31) lgkmcnt(0)
	v_lshlrev_b32_e32 v226, 16, v142
	v_and_b32_e32 v227, 0xffff0000, v142
	v_lshlrev_b32_e32 v228, 16, v143
	v_and_b32_e32 v229, 0xffff0000, v143
	v_mul_f32_e32 v44, v226, v44
	v_mul_f32_e32 v45, v227, v45
	v_mul_f32_e32 v46, v228, v46
	v_mul_f32_e32 v47, v229, v47
	v_cvt_pk_bf16_f32 v44, v44, v45
	v_cvt_pk_bf16_f32 v45, v46, v47
	global_store_dwordx2 v225, v[44:45], s[56:57]
	v_add_u32_e32 v225, 0x5000, v225
	ds_write_b32 v222, v16
	ds_write_b32 v222, v17 offset:256
	ds_write_b32 v222, v18 offset:512
	ds_write_b32 v222, v19 offset:768
	ds_write_b32 v222, v20 offset:2048
	ds_write_b32 v222, v21 offset:2304
	ds_write_b32 v222, v22 offset:2560
	ds_write_b32 v222, v23 offset:2816
	ds_write_b32 v222, v24 offset:4096
	ds_write_b32 v222, v25 offset:4352
	ds_write_b32 v222, v26 offset:4608
	ds_write_b32 v222, v27 offset:4864
	ds_write_b32 v222, v28 offset:6144
	ds_write_b32 v222, v29 offset:6400
	ds_write_b32 v222, v30 offset:6656
	ds_write_b32 v222, v31 offset:6912
	ds_write_b32 v222, v80 offset:128
	ds_write_b32 v222, v81 offset:384
	ds_write_b32 v222, v82 offset:640
	ds_write_b32 v222, v83 offset:896
	ds_write_b32 v222, v84 offset:2176
	ds_write_b32 v222, v85 offset:2432
	ds_write_b32 v222, v86 offset:2688
	ds_write_b32 v222, v87 offset:2944
	ds_write_b32 v222, v88 offset:4224
	ds_write_b32 v222, v89 offset:4480
	ds_write_b32 v222, v90 offset:4736
	ds_write_b32 v222, v91 offset:4992
	ds_write_b32 v222, v92 offset:6272
	ds_write_b32 v222, v93 offset:6528
	ds_write_b32 v222, v94 offset:6784
	ds_write_b32 v222, v95 offset:7040
	s_waitcnt lgkmcnt(0)
	ds_read_b128 v[16:19], v223
	ds_read_b128 v[20:23], v223 offset:1024
	ds_read_b128 v[24:27], v223 offset:2048
	ds_read_b128 v[28:31], v223 offset:3072
	ds_read_b128 v[80:83], v223 offset:4096
	ds_read_b128 v[84:87], v223 offset:5120
	ds_read_b128 v[88:91], v223 offset:6144
	ds_read_b128 v[92:95], v223 offset:7168
	s_waitcnt vmcnt(31) lgkmcnt(7)
	v_lshlrev_b32_e32 v226, 16, v144
	v_and_b32_e32 v227, 0xffff0000, v144
	v_lshlrev_b32_e32 v228, 16, v145
	v_and_b32_e32 v229, 0xffff0000, v145
	v_mul_f32_e32 v16, v226, v16
	v_mul_f32_e32 v17, v227, v17
	v_mul_f32_e32 v18, v228, v18
	v_mul_f32_e32 v19, v229, v19
	v_cvt_pk_bf16_f32 v16, v16, v17
	v_cvt_pk_bf16_f32 v17, v18, v19
	global_store_dwordx2 v225, v[16:17], s[56:57]
	v_add_u32_e32 v225, 0x5000, v225
	s_waitcnt vmcnt(31) lgkmcnt(6)
	v_lshlrev_b32_e32 v226, 16, v146
	v_and_b32_e32 v227, 0xffff0000, v146
	v_lshlrev_b32_e32 v228, 16, v147
	v_and_b32_e32 v229, 0xffff0000, v147
	v_mul_f32_e32 v20, v226, v20
	v_mul_f32_e32 v21, v227, v21
	v_mul_f32_e32 v22, v228, v22
	v_mul_f32_e32 v23, v229, v23
	v_cvt_pk_bf16_f32 v20, v20, v21
	v_cvt_pk_bf16_f32 v21, v22, v23
	global_store_dwordx2 v225, v[20:21], s[56:57]
	v_add_u32_e32 v225, 0x5000, v225
	s_waitcnt vmcnt(31) lgkmcnt(5)
; DEV u16 f2bf(float f) { return (u16)(pack2(f, f) & 0xffffu); }
; DEV float bf2f(u16 h) { return __uint_as_float(((unsigned)h) << 16); }
; DEV void phase_p3a(const Params& p, int g, char* smem) {
;     ...
;     acc_foreach(acc, m0, n0, [&](int m, int n, float& v) {
;       const float gb = bf2f(GT[(size_t)m * 2048 + 1024 + n]);
;       PHG[(size_t)m * 2560 + 1024 + n] = f2bf(gb * v);
;     });
	v_lshlrev_b32_e32 v226, 16, v148
	v_and_b32_e32 v227, 0xffff0000, v148
	v_lshlrev_b32_e32 v228, 16, v149
	v_and_b32_e32 v229, 0xffff0000, v149
	v_mul_f32_e32 v24, v226, v24
	v_mul_f32_e32 v25, v227, v25
	v_mul_f32_e32 v26, v228, v26
	v_mul_f32_e32 v27, v229, v27
	v_cvt_pk_bf16_f32 v24, v24, v25
	v_cvt_pk_bf16_f32 v25, v26, v27
	global_store_dwordx2 v225, v[24:25], s[56:57]
	v_add_u32_e32 v225, 0x5000, v225
	s_waitcnt vmcnt(31) lgkmcnt(4)
	v_lshlrev_b32_e32 v226, 16, v150
	v_and_b32_e32 v227, 0xffff0000, v150
	v_lshlrev_b32_e32 v228, 16, v151
	v_and_b32_e32 v229, 0xffff0000, v151
	v_mul_f32_e32 v28, v226, v28
	v_mul_f32_e32 v29, v227, v29
	v_mul_f32_e32 v30, v228, v30
	v_mul_f32_e32 v31, v229, v31
	v_cvt_pk_bf16_f32 v28, v28, v29
	v_cvt_pk_bf16_f32 v29, v30, v31
	global_store_dwordx2 v225, v[28:29], s[56:57]
	v_add_u32_e32 v225, 0x5000, v225
	s_waitcnt vmcnt(31) lgkmcnt(3)
	v_lshlrev_b32_e32 v226, 16, v152
	v_and_b32_e32 v227, 0xffff0000, v152
	v_lshlrev_b32_e32 v228, 16, v153
	v_and_b32_e32 v229, 0xffff0000, v153
	v_mul_f32_e32 v80, v226, v80
	v_mul_f32_e32 v81, v227, v81
	v_mul_f32_e32 v82, v228, v82
	v_mul_f32_e32 v83, v229, v83
	v_cvt_pk_bf16_f32 v80, v80, v81
	v_cvt_pk_bf16_f32 v81, v82, v83
	global_store_dwordx2 v225, v[80:81], s[56:57]
	v_add_u32_e32 v225, 0x5000, v225
	s_waitcnt vmcnt(31) lgkmcnt(2)
	v_lshlrev_b32_e32 v226, 16, v154
	v_and_b32_e32 v227, 0xffff0000, v154
	v_lshlrev_b32_e32 v228, 16, v155
	v_and_b32_e32 v229, 0xffff0000, v155
	v_mul_f32_e32 v84, v226, v84
	v_mul_f32_e32 v85, v227, v85
	v_mul_f32_e32 v86, v228, v86
	v_mul_f32_e32 v87, v229, v87
	v_cvt_pk_bf16_f32 v84, v84, v85
	v_cvt_pk_bf16_f32 v85, v86, v87
	global_store_dwordx2 v225, v[84:85], s[56:57]
	v_add_u32_e32 v225, 0x5000, v225
	s_waitcnt vmcnt(31) lgkmcnt(1)
	v_lshlrev_b32_e32 v226, 16, v156
	v_and_b32_e32 v227, 0xffff0000, v156
	v_lshlrev_b32_e32 v228, 16, v157
	v_and_b32_e32 v229, 0xffff0000, v157
	v_mul_f32_e32 v88, v226, v88
	v_mul_f32_e32 v89, v227, v89
	v_mul_f32_e32 v90, v228, v90
	v_mul_f32_e32 v91, v229, v91
	v_cvt_pk_bf16_f32 v88, v88, v89
	v_cvt_pk_bf16_f32 v89, v90, v91
	global_store_dwordx2 v225, v[88:89], s[56:57]
	v_add_u32_e32 v225, 0x5000, v225
	s_waitcnt vmcnt(31) lgkmcnt(0)
	v_lshlrev_b32_e32 v226, 16, v158
	v_and_b32_e32 v227, 0xffff0000, v158
	v_lshlrev_b32_e32 v228, 16, v159
	v_and_b32_e32 v229, 0xffff0000, v159
	v_mul_f32_e32 v92, v226, v92
	v_mul_f32_e32 v93, v227, v93
	v_mul_f32_e32 v94, v228, v94
	v_mul_f32_e32 v95, v229, v95
	v_cvt_pk_bf16_f32 v92, v92, v93
	v_cvt_pk_bf16_f32 v93, v94, v95
	global_store_dwordx2 v225, v[92:93], s[56:57]
	v_add_u32_e32 v225, 0x5000, v225
	ds_write_b32 v222, v48
	ds_write_b32 v222, v49 offset:256
	ds_write_b32 v222, v50 offset:512
	ds_write_b32 v222, v51 offset:768
	ds_write_b32 v222, v52 offset:2048
	ds_write_b32 v222, v53 offset:2304
	ds_write_b32 v222, v54 offset:2560
	ds_write_b32 v222, v55 offset:2816
	ds_write_b32 v222, v56 offset:4096
	ds_write_b32 v222, v57 offset:4352
	ds_write_b32 v222, v58 offset:4608
	ds_write_b32 v222, v59 offset:4864
	ds_write_b32 v222, v60 offset:6144
	ds_write_b32 v222, v61 offset:6400
	ds_write_b32 v222, v62 offset:6656
	ds_write_b32 v222, v63 offset:6912
	ds_write_b32 v222, v112 offset:128
	ds_write_b32 v222, v113 offset:384
	ds_write_b32 v222, v114 offset:640
	ds_write_b32 v222, v115 offset:896
	ds_write_b32 v222, v116 offset:2176
	ds_write_b32 v222, v117 offset:2432
	ds_write_b32 v222, v118 offset:2688
	ds_write_b32 v222, v119 offset:2944
	ds_write_b32 v222, v120 offset:4224
	ds_write_b32 v222, v121 offset:4480
	ds_write_b32 v222, v122 offset:4736
	ds_write_b32 v222, v123 offset:4992
	ds_write_b32 v222, v124 offset:6272
	ds_write_b32 v222, v125 offset:6528
	ds_write_b32 v222, v126 offset:6784
	ds_write_b32 v222, v127 offset:7040
	s_waitcnt lgkmcnt(0)
	ds_read_b128 v[48:51], v223
	ds_read_b128 v[52:55], v223 offset:1024
	ds_read_b128 v[56:59], v223 offset:2048
	ds_read_b128 v[60:63], v223 offset:3072
	ds_read_b128 v[112:115], v223 offset:4096
	ds_read_b128 v[116:119], v223 offset:5120
	ds_read_b128 v[120:123], v223 offset:6144
	ds_read_b128 v[124:127], v223 offset:7168
	s_waitcnt vmcnt(31) lgkmcnt(7)
	v_lshlrev_b32_e32 v226, 16, v170
	v_and_b32_e32 v227, 0xffff0000, v170
	v_lshlrev_b32_e32 v228, 16, v171
	v_and_b32_e32 v229, 0xffff0000, v171
	v_mul_f32_e32 v48, v226, v48
	v_mul_f32_e32 v49, v227, v49
	v_mul_f32_e32 v50, v228, v50
	v_mul_f32_e32 v51, v229, v51
	v_cvt_pk_bf16_f32 v48, v48, v49
	v_cvt_pk_bf16_f32 v49, v50, v51
	global_store_dwordx2 v225, v[48:49], s[56:57]
	v_add_u32_e32 v225, 0x5000, v225
	s_waitcnt vmcnt(31) lgkmcnt(6)
	v_lshlrev_b32_e32 v226, 16, v172
	v_and_b32_e32 v227, 0xffff0000, v172
	v_lshlrev_b32_e32 v228, 16, v173
	v_and_b32_e32 v229, 0xffff0000, v173
	v_mul_f32_e32 v52, v226, v52
	v_mul_f32_e32 v53, v227, v53
	v_mul_f32_e32 v54, v228, v54
	v_mul_f32_e32 v55, v229, v55
	v_cvt_pk_bf16_f32 v52, v52, v53
	v_cvt_pk_bf16_f32 v53, v54, v55
	global_store_dwordx2 v225, v[52:53], s[56:57]
	v_add_u32_e32 v225, 0x5000, v225
	s_waitcnt vmcnt(31) lgkmcnt(5)
	v_lshlrev_b32_e32 v226, 16, v174
	v_and_b32_e32 v227, 0xffff0000, v174
	v_lshlrev_b32_e32 v228, 16, v175
	v_and_b32_e32 v229, 0xffff0000, v175
	v_mul_f32_e32 v56, v226, v56
	v_mul_f32_e32 v57, v227, v57
	v_mul_f32_e32 v58, v228, v58
	v_mul_f32_e32 v59, v229, v59
	v_cvt_pk_bf16_f32 v56, v56, v57
	v_cvt_pk_bf16_f32 v57, v58, v59
	global_store_dwordx2 v225, v[56:57], s[56:57]
	v_add_u32_e32 v225, 0x5000, v225
	s_waitcnt vmcnt(31) lgkmcnt(4)
; DEV u16 f2bf(float f) { return (u16)(pack2(f, f) & 0xffffu); }
; DEV float bf2f(u16 h) { return __uint_as_float(((unsigned)h) << 16); }
; DEV void phase_p3a(const Params& p, int g, char* smem) {
;     ...
;     acc_foreach(acc, m0, n0, [&](int m, int n, float& v) {
;       const float gb = bf2f(GT[(size_t)m * 2048 + 1024 + n]);
;       PHG[(size_t)m * 2560 + 1024 + n] = f2bf(gb * v);
;     });
	v_lshlrev_b32_e32 v226, 16, v176
	v_and_b32_e32 v227, 0xffff0000, v176
	v_lshlrev_b32_e32 v228, 16, v177
	v_and_b32_e32 v229, 0xffff0000, v177
	v_mul_f32_e32 v60, v226, v60
	v_mul_f32_e32 v61, v227, v61
	v_mul_f32_e32 v62, v228, v62
	v_mul_f32_e32 v63, v229, v63
	v_cvt_pk_bf16_f32 v60, v60, v61
	v_cvt_pk_bf16_f32 v61, v62, v63
	global_store_dwordx2 v225, v[60:61], s[56:57]
	v_add_u32_e32 v225, 0x5000, v225
	s_waitcnt vmcnt(31) lgkmcnt(3)
	v_lshlrev_b32_e32 v226, 16, v178
	v_and_b32_e32 v227, 0xffff0000, v178
	v_lshlrev_b32_e32 v228, 16, v179
	v_and_b32_e32 v229, 0xffff0000, v179
	v_mul_f32_e32 v112, v226, v112
	v_mul_f32_e32 v113, v227, v113
	v_mul_f32_e32 v114, v228, v114
	v_mul_f32_e32 v115, v229, v115
	v_cvt_pk_bf16_f32 v112, v112, v113
	v_cvt_pk_bf16_f32 v113, v114, v115
	global_store_dwordx2 v225, v[112:113], s[56:57]
	v_add_u32_e32 v225, 0x5000, v225
	s_waitcnt vmcnt(31) lgkmcnt(2)
	v_lshlrev_b32_e32 v226, 16, v180
	v_and_b32_e32 v227, 0xffff0000, v180
	v_lshlrev_b32_e32 v228, 16, v181
	v_and_b32_e32 v229, 0xffff0000, v181
	v_mul_f32_e32 v116, v226, v116
	v_mul_f32_e32 v117, v227, v117
	v_mul_f32_e32 v118, v228, v118
	v_mul_f32_e32 v119, v229, v119
	v_cvt_pk_bf16_f32 v116, v116, v117
	v_cvt_pk_bf16_f32 v117, v118, v119
	global_store_dwordx2 v225, v[116:117], s[56:57]
	v_add_u32_e32 v225, 0x5000, v225
	s_waitcnt vmcnt(31) lgkmcnt(1)
	v_lshlrev_b32_e32 v226, 16, v182
	v_and_b32_e32 v227, 0xffff0000, v182
	v_lshlrev_b32_e32 v228, 16, v183
	v_and_b32_e32 v229, 0xffff0000, v183
	v_mul_f32_e32 v120, v226, v120
	v_mul_f32_e32 v121, v227, v121
	v_mul_f32_e32 v122, v228, v122
	v_mul_f32_e32 v123, v229, v123
	v_cvt_pk_bf16_f32 v120, v120, v121
	v_cvt_pk_bf16_f32 v121, v122, v123
	global_store_dwordx2 v225, v[120:121], s[56:57]
	v_add_u32_e32 v225, 0x5000, v225
	s_waitcnt vmcnt(31) lgkmcnt(0)
	v_lshlrev_b32_e32 v226, 16, v184
	v_and_b32_e32 v227, 0xffff0000, v184
	v_lshlrev_b32_e32 v228, 16, v185
	v_and_b32_e32 v229, 0xffff0000, v185
	v_mul_f32_e32 v124, v226, v124
	v_mul_f32_e32 v125, v227, v125
	v_mul_f32_e32 v126, v228, v126
	v_mul_f32_e32 v127, v229, v127
	v_cvt_pk_bf16_f32 v124, v124, v125
	v_cvt_pk_bf16_f32 v125, v126, v127
	global_store_dwordx2 v225, v[124:125], s[56:57]
	v_add_u32_e32 v225, 0x5000, v225
	ds_write_b32 v222, v96
	ds_write_b32 v222, v97 offset:256
	ds_write_b32 v222, v98 offset:512
	ds_write_b32 v222, v99 offset:768
	ds_write_b32 v222, v100 offset:2048
	ds_write_b32 v222, v101 offset:2304
	ds_write_b32 v222, v102 offset:2560
	ds_write_b32 v222, v103 offset:2816
	ds_write_b32 v222, v104 offset:4096
	ds_write_b32 v222, v105 offset:4352
	ds_write_b32 v222, v106 offset:4608
	ds_write_b32 v222, v107 offset:4864
	ds_write_b32 v222, v108 offset:6144
	ds_write_b32 v222, v109 offset:6400
	ds_write_b32 v222, v110 offset:6656
	ds_write_b32 v222, v111 offset:6912
	ds_write_b32 v222, v64 offset:128
	ds_write_b32 v222, v65 offset:384
	ds_write_b32 v222, v66 offset:640
	ds_write_b32 v222, v67 offset:896
	ds_write_b32 v222, v68 offset:2176
	ds_write_b32 v222, v69 offset:2432
	ds_write_b32 v222, v70 offset:2688
	ds_write_b32 v222, v71 offset:2944
	ds_write_b32 v222, v72 offset:4224
	ds_write_b32 v222, v73 offset:4480
	ds_write_b32 v222, v74 offset:4736
	ds_write_b32 v222, v75 offset:4992
	ds_write_b32 v222, v76 offset:6272
	ds_write_b32 v222, v77 offset:6528
	ds_write_b32 v222, v78 offset:6784
	ds_write_b32 v222, v79 offset:7040
	s_waitcnt lgkmcnt(0)
	ds_read_b128 v[96:99], v223
	ds_read_b128 v[100:103], v223 offset:1024
	ds_read_b128 v[104:107], v223 offset:2048
	ds_read_b128 v[108:111], v223 offset:3072
	ds_read_b128 v[64:67], v223 offset:4096
	ds_read_b128 v[68:71], v223 offset:5120
	ds_read_b128 v[72:75], v223 offset:6144
	ds_read_b128 v[76:79], v223 offset:7168
	s_waitcnt vmcnt(31) lgkmcnt(7)
; DEV u16 f2bf(float f) { return (u16)(pack2(f, f) & 0xffffu); }
; DEV float bf2f(u16 h) { return __uint_as_float(((unsigned)h) << 16); }
; DEV void phase_p3a(const Params& p, int g, char* smem) {
;     ...
;     acc_foreach(acc, m0, n0, [&](int m, int n, float& v) {
;       const float gb = bf2f(GT[(size_t)m * 2048 + 1024 + n]);
;       PHG[(size_t)m * 2560 + 1024 + n] = f2bf(gb * v);
;     });
	v_lshlrev_b32_e32 v226, 16, v186
	v_and_b32_e32 v227, 0xffff0000, v186
	v_lshlrev_b32_e32 v228, 16, v187
	v_and_b32_e32 v229, 0xffff0000, v187
	v_mul_f32_e32 v96, v226, v96
	v_mul_f32_e32 v97, v227, v97
	v_mul_f32_e32 v98, v228, v98
	v_mul_f32_e32 v99, v229, v99
	v_cvt_pk_bf16_f32 v96, v96, v97
	v_cvt_pk_bf16_f32 v97, v98, v99
	global_store_dwordx2 v225, v[96:97], s[56:57]
	v_add_u32_e32 v225, 0x5000, v225
	s_waitcnt vmcnt(31) lgkmcnt(6)
	v_lshlrev_b32_e32 v226, 16, v188
	v_and_b32_e32 v227, 0xffff0000, v188
	v_lshlrev_b32_e32 v228, 16, v189
	v_and_b32_e32 v229, 0xffff0000, v189
	v_mul_f32_e32 v100, v226, v100
	v_mul_f32_e32 v101, v227, v101
	v_mul_f32_e32 v102, v228, v102
	v_mul_f32_e32 v103, v229, v103
	v_cvt_pk_bf16_f32 v100, v100, v101
	v_cvt_pk_bf16_f32 v101, v102, v103
	global_store_dwordx2 v225, v[100:101], s[56:57]
	v_add_u32_e32 v225, 0x5000, v225
	s_waitcnt vmcnt(31) lgkmcnt(5)
	v_lshlrev_b32_e32 v226, 16, v190
	v_and_b32_e32 v227, 0xffff0000, v190
	v_lshlrev_b32_e32 v228, 16, v191
	v_and_b32_e32 v229, 0xffff0000, v191
	v_mul_f32_e32 v104, v226, v104
	v_mul_f32_e32 v105, v227, v105
	v_mul_f32_e32 v106, v228, v106
	v_mul_f32_e32 v107, v229, v107
	v_cvt_pk_bf16_f32 v104, v104, v105
	v_cvt_pk_bf16_f32 v105, v106, v107
	global_store_dwordx2 v225, v[104:105], s[56:57]
	v_add_u32_e32 v225, 0x5000, v225
	s_waitcnt vmcnt(31) lgkmcnt(4)
	v_lshlrev_b32_e32 v226, 16, v192
	v_and_b32_e32 v227, 0xffff0000, v192
	v_lshlrev_b32_e32 v228, 16, v193
	v_and_b32_e32 v229, 0xffff0000, v193
	v_mul_f32_e32 v108, v226, v108
	v_mul_f32_e32 v109, v227, v109
	v_mul_f32_e32 v110, v228, v110
	v_mul_f32_e32 v111, v229, v111
	v_cvt_pk_bf16_f32 v108, v108, v109
	v_cvt_pk_bf16_f32 v109, v110, v111
	global_store_dwordx2 v225, v[108:109], s[56:57]
	v_add_u32_e32 v225, 0x5000, v225
	s_waitcnt vmcnt(31) lgkmcnt(3)
	v_lshlrev_b32_e32 v226, 16, v194
	v_and_b32_e32 v227, 0xffff0000, v194
	v_lshlrev_b32_e32 v228, 16, v195
	v_and_b32_e32 v229, 0xffff0000, v195
	v_mul_f32_e32 v64, v226, v64
	v_mul_f32_e32 v65, v227, v65
	v_mul_f32_e32 v66, v228, v66
	v_mul_f32_e32 v67, v229, v67
	v_cvt_pk_bf16_f32 v64, v64, v65
	v_cvt_pk_bf16_f32 v65, v66, v67
	global_store_dwordx2 v225, v[64:65], s[56:57]
	v_add_u32_e32 v225, 0x5000, v225
	s_waitcnt vmcnt(31) lgkmcnt(2)
	v_lshlrev_b32_e32 v226, 16, v196
	v_and_b32_e32 v227, 0xffff0000, v196
	v_lshlrev_b32_e32 v228, 16, v197
	v_and_b32_e32 v229, 0xffff0000, v197
	v_mul_f32_e32 v68, v226, v68
	v_mul_f32_e32 v69, v227, v69
	v_mul_f32_e32 v70, v228, v70
	v_mul_f32_e32 v71, v229, v71
	v_cvt_pk_bf16_f32 v68, v68, v69
	v_cvt_pk_bf16_f32 v69, v70, v71
	global_store_dwordx2 v225, v[68:69], s[56:57]
	v_add_u32_e32 v225, 0x5000, v225
	s_waitcnt vmcnt(31) lgkmcnt(1)
	v_lshlrev_b32_e32 v226, 16, v198
	v_and_b32_e32 v227, 0xffff0000, v198
	v_lshlrev_b32_e32 v228, 16, v199
	v_and_b32_e32 v229, 0xffff0000, v199
	v_mul_f32_e32 v72, v226, v72
	v_mul_f32_e32 v73, v227, v73
	v_mul_f32_e32 v74, v228, v74
	v_mul_f32_e32 v75, v229, v75
	v_cvt_pk_bf16_f32 v72, v72, v73
	v_cvt_pk_bf16_f32 v73, v74, v75
	global_store_dwordx2 v225, v[72:73], s[56:57]
	v_add_u32_e32 v225, 0x5000, v225
	s_waitcnt vmcnt(31) lgkmcnt(0)
	v_lshlrev_b32_e32 v226, 16, v200
	v_and_b32_e32 v227, 0xffff0000, v200
	v_lshlrev_b32_e32 v228, 16, v201
	v_and_b32_e32 v229, 0xffff0000, v201
	v_mul_f32_e32 v76, v226, v76
	v_mul_f32_e32 v77, v227, v77
	v_mul_f32_e32 v78, v228, v78
	v_mul_f32_e32 v79, v229, v79
	v_cvt_pk_bf16_f32 v76, v76, v77
	v_cvt_pk_bf16_f32 v77, v78, v79
	global_store_dwordx2 v225, v[76:77], s[56:57]
	v_add_u32_e32 v225, 0x5000, v225
	s_mov_b64 s[2:3], 0
	s_branch .LBB0_927

; template <class AL, class BL>
; DEV void gemm_mainloop(Acc& acc, const AL& al, const BL& bl, int m0, int n0, int kbeg, int kend, char* lds) {
;   const int tid = tidx_full();
;   const int wave = tid >> 6, lane = tid & 63;
;   const int wm = (wave >> 2) * 128, wn = (wave & 3) * 64;
;   const int lr = lane & 31, lh = lane >> 5;
;   const int nk = (kend - kbeg) / BK;
;   R4 a0 = al.load(tid, m0, kbeg);
;   R4 b0 = bl.load(tid, n0, kbeg);
;   __syncthreads();
;   al.store(tid, lds, a0);
;   bl.store(tid, lds + TILE_BYTES, b0);
;   a0 = al.load(tid, m0, kbeg + BK);
;   b0 = bl.load(tid, n0, kbeg + BK);
;   __syncthreads();
; DEV void phase_ff2(const Params& p, int g, char* smem) {
;     ...
;   for (int iter = 0;; ++iter) {
;     int mt, nt;
;     if (!tile_map(iter, 128, 4, mt, nt)) break;
;     const int m0 = mt * 256, n0 = nt * 256;
;     Acc acc;
;     acc_zero(acc);
;     RowLoader al{AB, 4096}, bl{W, 4096};
;     gemm_mainloop(acc, al, bl, m0, n0, 0, 4096, smem);
.LBB0_1192:
	s_lshl_b32 s3, s5, 8
	s_lshl_b32 s2, s6, 8
	v_readlane_b32 s0, v251, 30
	v_readlane_b32 s1, v251, 31
	s_mov_b64 s[6:7], s[74:75]
	v_lshrrev_b32_e32 v149, 6, v202
	v_and_b32_e32 v148, 63, v202
	s_nop 0
	v_readfirstlane_b32 s8, v149
	v_lshrrev_b32_e32 v150, 3, v148
	v_lshl_add_u32 v150, v149, 5, v150
	v_and_b32_e32 v151, 7, v148
	v_lshrrev_b32_e32 v128, 4, v148
	v_xor_b32_e32 v151, v128, v151
	v_lshlrev_b32_e32 v151, 4, v151
	s_lshl_b32 s8, s8, 12
	v_add_u32_e32 v128, s3, v150
	v_lshlrev_b32_e32 v128, 13, v128
	v_add_u32_e32 v128, v128, v151
	v_add_u32_e32 v129, 0x10000, v128
	v_add_u32_e32 v130, 0x20000, v128
	v_add_u32_e32 v131, 0x30000, v128
	v_xor_b32_e32 v129, 0x40, v129
	v_xor_b32_e32 v131, 0x40, v131
	v_add_u32_e32 v132, s2, v150
	v_lshlrev_b32_e32 v132, 13, v132
	v_add_u32_e32 v132, v132, v151
	v_add_u32_e32 v133, 0x10000, v132
	v_add_u32_e32 v134, 0x20000, v132
	v_add_u32_e32 v135, 0x30000, v132
	v_xor_b32_e32 v133, 0x40, v133
	v_xor_b32_e32 v135, 0x40, v135
	v_lshrrev_b32_e32 v150, 1, v148
	v_and_b32_e32 v150, 7, v150
	v_lshrrev_b32_e32 v151, 5, v148
	v_xor_b32_e32 v150, v150, v151
	v_lshlrev_b32_e32 v150, 4, v150
	v_and_b32_e32 v151, 31, v148
	v_lshlrev_b32_e32 v151, 7, v151
	v_lshrrev_b32_e32 v156, 2, v149
	v_lshl_add_u32 v156, v156, 14, v151
	v_and_b32_e32 v207, 3, v149
	v_lshl_add_u32 v207, v207, 13, v151
	v_add_u32_e32 v207, 0x10000, v207
	v_xor_b32_e32 v159, 0x60, v150
	v_add_u32_e32 v159, v156, v159
	v_xor_b32_e32 v158, 0x40, v150
	v_add_u32_e32 v158, v156, v158
	v_xor_b32_e32 v157, 0x20, v150
	v_add_u32_e32 v157, v156, v157
	v_add_u32_e32 v156, v156, v150
	v_xor_b32_e32 v210, 0x60, v150
	v_add_u32_e32 v210, v207, v210
	v_xor_b32_e32 v209, 0x40, v150
	v_add_u32_e32 v209, v207, v209
	v_xor_b32_e32 v208, 0x20, v150
	v_add_u32_e32 v208, v207, v208
	v_add_u32_e32 v207, v207, v150
	v_add_u32_e32 v136, 0x100000, v128
	v_add_u32_e32 v137, 0x100000, v129
	v_add_u32_e32 v138, 0x100000, v130
	v_add_u32_e32 v139, 0x100000, v131
	v_add_u32_e32 v140, 0x100000, v132
	v_add_u32_e32 v141, 0x100000, v133
	v_add_u32_e32 v142, 0x100000, v134
	v_add_u32_e32 v143, 0x100000, v135
	v_lshrrev_b32_e32 v149, 6, v202
	v_and_b32_e32 v148, 63, v202
	v_bfe_u32 v150, v148, 1, 3
	v_lshrrev_b32_e32 v151, 4, v148
	v_xor_b32_e32 v150, v150, v151
	v_lshlrev_b32_e32 v150, 4, v150
	v_and_b32_e32 v151, 15, v148
	v_lshlrev_b32_e32 v151, 7, v151
	v_lshrrev_b32_e32 v144, 2, v149
	v_lshl_add_u32 v144, v144, 14, v151
	v_and_b32_e32 v146, 3, v149
	v_lshl_add_u32 v146, v146, 13, v151
	v_add_u32_e32 v146, 0x10000, v146
	v_xor_b32_e32 v145, 0x40, v150
	v_add_u32_e32 v145, v144, v145
	v_add_u32_e32 v144, v144, v150
	v_xor_b32_e32 v147, 0x40, v150
	v_add_u32_e32 v147, v146, v147
	v_add_u32_e32 v146, v146, v150
	v_mov_b32_e32 v0, 0
	v_mov_b32_e32 v1, 0
	v_mov_b64_e32 v[2:3], v[0:1]
	v_mov_b64_e32 v[4:5], v[0:1]
	v_mov_b64_e32 v[6:7], v[0:1]
	v_mov_b64_e32 v[8:9], v[0:1]
	v_mov_b64_e32 v[10:11], v[0:1]
	v_mov_b64_e32 v[12:13], v[0:1]
	v_mov_b64_e32 v[14:15], v[0:1]
	v_mov_b64_e32 v[16:17], v[0:1]
	v_mov_b64_e32 v[18:19], v[0:1]
	v_mov_b64_e32 v[20:21], v[0:1]
	v_mov_b64_e32 v[22:23], v[0:1]
	v_mov_b64_e32 v[24:25], v[0:1]
	v_mov_b64_e32 v[26:27], v[0:1]
	v_mov_b64_e32 v[28:29], v[0:1]
	v_mov_b64_e32 v[30:31], v[0:1]
	v_mov_b64_e32 v[32:33], v[0:1]
	v_mov_b64_e32 v[34:35], v[0:1]
	v_mov_b64_e32 v[36:37], v[0:1]
	v_mov_b64_e32 v[38:39], v[0:1]
	v_mov_b64_e32 v[40:41], v[0:1]
	v_mov_b64_e32 v[42:43], v[0:1]
	v_mov_b64_e32 v[44:45], v[0:1]
	v_mov_b64_e32 v[46:47], v[0:1]
	v_mov_b64_e32 v[48:49], v[0:1]
	v_mov_b64_e32 v[50:51], v[0:1]
	v_mov_b64_e32 v[52:53], v[0:1]
	v_mov_b64_e32 v[54:55], v[0:1]
	v_mov_b64_e32 v[56:57], v[0:1]
	v_mov_b64_e32 v[58:59], v[0:1]
	v_mov_b64_e32 v[60:61], v[0:1]
	v_mov_b64_e32 v[62:63], v[0:1]
	v_mov_b64_e32 v[64:65], v[0:1]
	v_mov_b64_e32 v[66:67], v[0:1]
	v_mov_b64_e32 v[68:69], v[0:1]
	v_mov_b64_e32 v[70:71], v[0:1]
	v_mov_b64_e32 v[72:73], v[0:1]
	v_mov_b64_e32 v[74:75], v[0:1]
	v_mov_b64_e32 v[76:77], v[0:1]
	v_mov_b64_e32 v[78:79], v[0:1]
	v_mov_b64_e32 v[80:81], v[0:1]
	v_mov_b64_e32 v[82:83], v[0:1]
	v_mov_b64_e32 v[84:85], v[0:1]
	v_mov_b64_e32 v[86:87], v[0:1]
	v_mov_b64_e32 v[88:89], v[0:1]
	v_mov_b64_e32 v[90:91], v[0:1]
	v_mov_b64_e32 v[92:93], v[0:1]
	v_mov_b64_e32 v[94:95], v[0:1]
	v_mov_b64_e32 v[96:97], v[0:1]
	v_mov_b64_e32 v[98:99], v[0:1]
	v_mov_b64_e32 v[100:101], v[0:1]
	v_mov_b64_e32 v[102:103], v[0:1]
	v_mov_b64_e32 v[104:105], v[0:1]
	v_mov_b64_e32 v[106:107], v[0:1]
	v_mov_b64_e32 v[108:109], v[0:1]
	v_mov_b64_e32 v[110:111], v[0:1]
	v_mov_b64_e32 v[112:113], v[0:1]
	v_mov_b64_e32 v[114:115], v[0:1]
	v_mov_b64_e32 v[116:117], v[0:1]
	v_mov_b64_e32 v[118:119], v[0:1]
	v_mov_b64_e32 v[120:121], v[0:1]
	v_mov_b64_e32 v[122:123], v[0:1]
	v_mov_b64_e32 v[124:125], v[0:1]
	v_mov_b64_e32 v[126:127], v[0:1]
	s_cmp_lt_u32 s8, 0x4000
	s_cbranch_scc0 .Lff2_d1
	s_add_u32 m0, s8, 0x0
	s_nop 0
	global_load_lds_dwordx4 v128, s[6:7]
	s_add_u32 m0, m0, 0x400
	s_nop 0
	global_load_lds_dwordx4 v129, s[6:7]
	s_add_u32 m0, m0, 0x400
	s_nop 0
	global_load_lds_dwordx4 v130, s[6:7]
	s_add_u32 m0, m0, 0x400
	s_nop 0
	global_load_lds_dwordx4 v131, s[6:7]
	s_add_u32 m0, s8, 0x10000
	s_nop 0
	global_load_lds_dwordx4 v132, s[0:1]
	s_add_u32 m0, m0, 0x400
	s_nop 0
	global_load_lds_dwordx4 v133, s[0:1]
	s_add_u32 m0, m0, 0x400
	s_nop 0
	global_load_lds_dwordx4 v134, s[0:1]
	s_add_u32 m0, m0, 0x400
	s_nop 0
	global_load_lds_dwordx4 v135, s[0:1]
	s_add_u32 m0, s8, 0x4000
	s_nop 0
	global_load_lds_dwordx4 v136, s[6:7]
	s_add_u32 m0, m0, 0x400
	s_nop 0
	global_load_lds_dwordx4 v137, s[6:7]
	s_add_u32 m0, m0, 0x400
	s_nop 0
	global_load_lds_dwordx4 v138, s[6:7]
	s_add_u32 m0, m0, 0x400
	s_nop 0
	global_load_lds_dwordx4 v139, s[6:7]
	s_add_u32 m0, s8, 0x14000
	s_nop 0
	global_load_lds_dwordx4 v140, s[0:1]
	s_add_u32 m0, m0, 0x400
	s_nop 0
	global_load_lds_dwordx4 v141, s[0:1]
	s_add_u32 m0, m0, 0x400
	s_nop 0
	global_load_lds_dwordx4 v142, s[0:1]
	s_add_u32 m0, m0, 0x400
	s_nop 0
	global_load_lds_dwordx4 v143, s[0:1]
; template <class AL, class BL>
; DEV void gemm_ktile(Acc& acc, const char* A, const char* B, int wm, int wn, int lr, int lh, const AL& al, const BL& bl,
;                     int tid, int m0, int n0, int knext, char* nxt, R4& ra, R4& rb) {
;     ...
;   for (int ks = 0; ks < 4; ++ks) {
;     const int cur = ks & 1, nx = cur ^ 1;
;     if (ks < 3) {
; #pragma unroll
;       for (int i = 0; i < 4; ++i) a[nx][i] = *(const bf16x8*)(pa + 32 * i * LDSROW + (ks + 1) * 32);
; #pragma unroll
;       for (int j = 0; j < 2; ++j) b[nx][j] = *(const bf16x8*)(pb + 32 * j * LDSROW + (ks + 1) * 32);
;     }
;     __builtin_amdgcn_sched_barrier(0);
; #pragma unroll
;     for (int i = 0; i < 4; ++i)
; #pragma unroll
;       for (int j = 0; j < 2; ++j)
;         acc[i][j] = __builtin_amdgcn_mfma_f32_32x32x16_bf16(a[cur][i], b[cur][j], acc[i][j], 0, 0, 0);
; template <class AL, class BL>
; DEV void gemm_mainloop(Acc& acc, const AL& al, const BL& bl, int m0, int n0, int kbeg, int kend, char* lds) {
;     ...
;   for (int kt = 0; kt < nk; ++kt) {
;     const char* cur = lds + (kt & 1) * 2 * TILE_BYTES;
;     char* nxt = lds + ((kt + 1) & 1) * 2 * TILE_BYTES;
;     const int t2 = (kt + 2 < nk) ? kt + 2 : nk - 1;
;     __builtin_amdgcn_sched_barrier(0);
;     gemm_ktile(acc, cur, cur + TILE_BYTES, wm, wn, lr, lh, al, bl, tid, m0, n0, kbeg + t2 * BK, nxt, a0, b0);
;     __builtin_amdgcn_sched_barrier(0);
;     __syncthreads();
;   }
.Lff2_d1:
	s_add_u32 s6, s6, 0x80
	s_addc_u32 s7, s7, 0
	s_add_u32 s0, s0, 0x80
	s_addc_u32 s1, s1, 0
	s_mov_b32 s5, 0
	s_waitcnt vmcnt(0)
	s_barrier
.Lff2_kloop:
	s_cmp_lt_u32 s8, 0x4000
	s_cbranch_scc0 .Lff2_d2
	s_add_u32 m0, s8, 0x8000
	s_nop 0
	global_load_lds_dwordx4 v128, s[6:7]
	s_add_u32 m0, m0, 0x400
	s_nop 0
	global_load_lds_dwordx4 v129, s[6:7]
	s_add_u32 m0, m0, 0x400
	s_nop 0
	global_load_lds_dwordx4 v130, s[6:7]
	s_add_u32 m0, m0, 0x400
	s_nop 0
	global_load_lds_dwordx4 v131, s[6:7]
	s_add_u32 m0, s8, 0x18000
	s_nop 0
	global_load_lds_dwordx4 v132, s[0:1]
	s_add_u32 m0, m0, 0x400
	s_nop 0
	global_load_lds_dwordx4 v133, s[0:1]
	s_add_u32 m0, m0, 0x400
	s_nop 0
	global_load_lds_dwordx4 v134, s[0:1]
	s_add_u32 m0, m0, 0x400
	s_nop 0
	global_load_lds_dwordx4 v135, s[0:1]
	s_add_u32 m0, s8, 0xc000
	s_nop 0
	global_load_lds_dwordx4 v136, s[6:7]
	s_add_u32 m0, m0, 0x400
	s_nop 0
	global_load_lds_dwordx4 v137, s[6:7]
	s_add_u32 m0, m0, 0x400
	s_nop 0
	global_load_lds_dwordx4 v138, s[6:7]
	s_add_u32 m0, m0, 0x400
	s_nop 0
	global_load_lds_dwordx4 v139, s[6:7]
	s_add_u32 m0, s8, 0x1c000
	s_nop 0
	global_load_lds_dwordx4 v140, s[0:1]
	s_add_u32 m0, m0, 0x400
	s_nop 0
	global_load_lds_dwordx4 v141, s[0:1]
	s_add_u32 m0, m0, 0x400
	s_nop 0
	global_load_lds_dwordx4 v142, s[0:1]
	s_add_u32 m0, m0, 0x400
	s_nop 0
	global_load_lds_dwordx4 v143, s[0:1]
.Lff2_d2:
	s_add_u32 s6, s6, 0x80
	s_addc_u32 s7, s7, 0
	s_add_u32 s0, s0, 0x80
	s_addc_u32 s1, s1, 0
	ds_read_b128 v[166:169], v146
	ds_read_b128 v[170:173], v146 offset:2048
	ds_read_b128 v[174:177], v146 offset:4096
	ds_read_b128 v[178:181], v146 offset:6144
	ds_read_b128 v[222:225], v144
	ds_read_b128 v[226:229], v144 offset:2048
	ds_read_b128 v[230:233], v144 offset:4096
	ds_read_b128 v[234:237], v144 offset:6144
	ds_read_b128 v[238:241], v144 offset:8192
	ds_read_b128 v[242:245], v144 offset:10240
	ds_read_b128 v[198:201], v144 offset:12288
	ds_read_b128 v[152:155], v144 offset:14336
	ds_read_b128 v[182:185], v147
	ds_read_b128 v[186:189], v147 offset:2048
	ds_read_b128 v[190:193], v147 offset:4096
	ds_read_b128 v[194:197], v147 offset:6144
	s_waitcnt lgkmcnt(8)
	v_mfma_f32_16x16x32_bf16 v[0:3], v[166:169], v[222:225], v[0:3]
	v_mfma_f32_16x16x32_bf16 v[4:7], v[170:173], v[222:225], v[4:7]
	v_mfma_f32_16x16x32_bf16 v[8:11], v[174:177], v[222:225], v[8:11]
	v_mfma_f32_16x16x32_bf16 v[12:15], v[178:181], v[222:225], v[12:15]
	v_mfma_f32_16x16x32_bf16 v[16:19], v[166:169], v[226:229], v[16:19]
	v_mfma_f32_16x16x32_bf16 v[20:23], v[170:173], v[226:229], v[20:23]
	v_mfma_f32_16x16x32_bf16 v[24:27], v[174:177], v[226:229], v[24:27]
	v_mfma_f32_16x16x32_bf16 v[28:31], v[178:181], v[226:229], v[28:31]
	v_mfma_f32_16x16x32_bf16 v[32:35], v[166:169], v[230:233], v[32:35]
	v_mfma_f32_16x16x32_bf16 v[36:39], v[170:173], v[230:233], v[36:39]
	v_mfma_f32_16x16x32_bf16 v[40:43], v[174:177], v[230:233], v[40:43]
	v_mfma_f32_16x16x32_bf16 v[44:47], v[178:181], v[230:233], v[44:47]
	v_mfma_f32_16x16x32_bf16 v[48:51], v[166:169], v[234:237], v[48:51]
	v_mfma_f32_16x16x32_bf16 v[52:55], v[170:173], v[234:237], v[52:55]
	v_mfma_f32_16x16x32_bf16 v[56:59], v[174:177], v[234:237], v[56:59]
	v_mfma_f32_16x16x32_bf16 v[60:63], v[178:181], v[234:237], v[60:63]
	ds_read_b128 v[222:225], v145
	ds_read_b128 v[226:229], v145 offset:2048
	ds_read_b128 v[230:233], v145 offset:4096
	ds_read_b128 v[234:237], v145 offset:6144
	s_waitcnt lgkmcnt(8)
	v_mfma_f32_16x16x32_bf16 v[64:67], v[166:169], v[238:241], v[64:67]
	v_mfma_f32_16x16x32_bf16 v[68:71], v[170:173], v[238:241], v[68:71]
	v_mfma_f32_16x16x32_bf16 v[72:75], v[174:177], v[238:241], v[72:75]
	v_mfma_f32_16x16x32_bf16 v[76:79], v[178:181], v[238:241], v[76:79]
	v_mfma_f32_16x16x32_bf16 v[80:83], v[166:169], v[242:245], v[80:83]
	v_mfma_f32_16x16x32_bf16 v[84:87], v[170:173], v[242:245], v[84:87]
	v_mfma_f32_16x16x32_bf16 v[88:91], v[174:177], v[242:245], v[88:91]
	v_mfma_f32_16x16x32_bf16 v[92:95], v[178:181], v[242:245], v[92:95]
	v_mfma_f32_16x16x32_bf16 v[96:99], v[166:169], v[198:201], v[96:99]
	v_mfma_f32_16x16x32_bf16 v[100:103], v[170:173], v[198:201], v[100:103]
	v_mfma_f32_16x16x32_bf16 v[104:107], v[174:177], v[198:201], v[104:107]
	v_mfma_f32_16x16x32_bf16 v[108:111], v[178:181], v[198:201], v[108:111]
	v_mfma_f32_16x16x32_bf16 v[112:115], v[166:169], v[152:155], v[112:115]
	v_mfma_f32_16x16x32_bf16 v[116:119], v[170:173], v[152:155], v[116:119]
	v_mfma_f32_16x16x32_bf16 v[120:123], v[174:177], v[152:155], v[120:123]
	v_mfma_f32_16x16x32_bf16 v[124:127], v[178:181], v[152:155], v[124:127]
	ds_read_b128 v[238:241], v145 offset:8192
	ds_read_b128 v[242:245], v145 offset:10240
	ds_read_b128 v[198:201], v145 offset:12288
	ds_read_b128 v[152:155], v145 offset:14336
	s_waitcnt lgkmcnt(4)
	v_mfma_f32_16x16x32_bf16 v[0:3], v[182:185], v[222:225], v[0:3]
	v_mfma_f32_16x16x32_bf16 v[4:7], v[186:189], v[222:225], v[4:7]
	v_mfma_f32_16x16x32_bf16 v[8:11], v[190:193], v[222:225], v[8:11]
	v_mfma_f32_16x16x32_bf16 v[12:15], v[194:197], v[222:225], v[12:15]
	v_mfma_f32_16x16x32_bf16 v[16:19], v[182:185], v[226:229], v[16:19]
	v_mfma_f32_16x16x32_bf16 v[20:23], v[186:189], v[226:229], v[20:23]
	v_mfma_f32_16x16x32_bf16 v[24:27], v[190:193], v[226:229], v[24:27]
	v_mfma_f32_16x16x32_bf16 v[28:31], v[194:197], v[226:229], v[28:31]
	v_mfma_f32_16x16x32_bf16 v[32:35], v[182:185], v[230:233], v[32:35]
	v_mfma_f32_16x16x32_bf16 v[36:39], v[186:189], v[230:233], v[36:39]
	v_mfma_f32_16x16x32_bf16 v[40:43], v[190:193], v[230:233], v[40:43]
	v_mfma_f32_16x16x32_bf16 v[44:47], v[194:197], v[230:233], v[44:47]
	v_mfma_f32_16x16x32_bf16 v[48:51], v[182:185], v[234:237], v[48:51]
	v_mfma_f32_16x16x32_bf16 v[52:55], v[186:189], v[234:237], v[52:55]
	v_mfma_f32_16x16x32_bf16 v[56:59], v[190:193], v[234:237], v[56:59]
	v_mfma_f32_16x16x32_bf16 v[60:63], v[194:197], v[234:237], v[60:63]
	s_waitcnt lgkmcnt(0)
	v_mfma_f32_16x16x32_bf16 v[64:67], v[182:185], v[238:241], v[64:67]
	v_mfma_f32_16x16x32_bf16 v[68:71], v[186:189], v[238:241], v[68:71]
	v_mfma_f32_16x16x32_bf16 v[72:75], v[190:193], v[238:241], v[72:75]
	v_mfma_f32_16x16x32_bf16 v[76:79], v[194:197], v[238:241], v[76:79]
	v_mfma_f32_16x16x32_bf16 v[80:83], v[182:185], v[242:245], v[80:83]
	v_mfma_f32_16x16x32_bf16 v[84:87], v[186:189], v[242:245], v[84:87]
	v_mfma_f32_16x16x32_bf16 v[88:91], v[190:193], v[242:245], v[88:91]
	v_mfma_f32_16x16x32_bf16 v[92:95], v[194:197], v[242:245], v[92:95]
	v_mfma_f32_16x16x32_bf16 v[96:99], v[182:185], v[198:201], v[96:99]
	v_mfma_f32_16x16x32_bf16 v[100:103], v[186:189], v[198:201], v[100:103]
	v_mfma_f32_16x16x32_bf16 v[104:107], v[190:193], v[198:201], v[104:107]
	v_mfma_f32_16x16x32_bf16 v[108:111], v[194:197], v[198:201], v[108:111]
	v_mfma_f32_16x16x32_bf16 v[112:115], v[182:185], v[152:155], v[112:115]
	v_mfma_f32_16x16x32_bf16 v[116:119], v[186:189], v[152:155], v[116:119]
	v_mfma_f32_16x16x32_bf16 v[120:123], v[190:193], v[152:155], v[120:123]
	v_mfma_f32_16x16x32_bf16 v[124:127], v[194:197], v[152:155], v[124:127]
	s_waitcnt vmcnt(0)
	s_barrier
; template <class AL, class BL>
; DEV void gemm_ktile(Acc& acc, const char* A, const char* B, int wm, int wn, int lr, int lh, const AL& al, const BL& bl,
;                     int tid, int m0, int n0, int knext, char* nxt, R4& ra, R4& rb) {
;     ...
;   for (int ks = 0; ks < 4; ++ks) {
;     const int cur = ks & 1, nx = cur ^ 1;
;     if (ks < 3) {
; #pragma unroll
;       for (int i = 0; i < 4; ++i) a[nx][i] = *(const bf16x8*)(pa + 32 * i * LDSROW + (ks + 1) * 32);
; #pragma unroll
;       for (int j = 0; j < 2; ++j) b[nx][j] = *(const bf16x8*)(pb + 32 * j * LDSROW + (ks + 1) * 32);
;     }
;     __builtin_amdgcn_sched_barrier(0);
; #pragma unroll
;     for (int i = 0; i < 4; ++i)
; #pragma unroll
;       for (int j = 0; j < 2; ++j)
;         acc[i][j] = __builtin_amdgcn_mfma_f32_32x32x16_bf16(a[cur][i], b[cur][j], acc[i][j], 0, 0, 0);
; template <class AL, class BL>
; DEV void gemm_mainloop(Acc& acc, const AL& al, const BL& bl, int m0, int n0, int kbeg, int kend, char* lds) {
;     ...
;   for (int kt = 0; kt < nk; ++kt) {
;     const char* cur = lds + (kt & 1) * 2 * TILE_BYTES;
;     char* nxt = lds + ((kt + 1) & 1) * 2 * TILE_BYTES;
;     const int t2 = (kt + 2 < nk) ? kt + 2 : nk - 1;
;     __builtin_amdgcn_sched_barrier(0);
;     gemm_ktile(acc, cur, cur + TILE_BYTES, wm, wn, lr, lh, al, bl, tid, m0, n0, kbeg + t2 * BK, nxt, a0, b0);
;     __builtin_amdgcn_sched_barrier(0);
;     __syncthreads();
;   }
	s_cmp_eq_u32 s5, 31
	s_cbranch_scc1 .Lff2_last
	s_cmp_lt_u32 s8, 0x4000
	s_cbranch_scc0 .Lff2_d3
	s_add_u32 m0, s8, 0x0
	s_nop 0
	global_load_lds_dwordx4 v128, s[6:7]
	s_add_u32 m0, m0, 0x400
	s_nop 0
	global_load_lds_dwordx4 v129, s[6:7]
	s_add_u32 m0, m0, 0x400
	s_nop 0
	global_load_lds_dwordx4 v130, s[6:7]
	s_add_u32 m0, m0, 0x400
	s_nop 0
	global_load_lds_dwordx4 v131, s[6:7]
	s_add_u32 m0, s8, 0x10000
	s_nop 0
	global_load_lds_dwordx4 v132, s[0:1]
	s_add_u32 m0, m0, 0x400
	s_nop 0
	global_load_lds_dwordx4 v133, s[0:1]
	s_add_u32 m0, m0, 0x400
	s_nop 0
	global_load_lds_dwordx4 v134, s[0:1]
	s_add_u32 m0, m0, 0x400
	s_nop 0
	global_load_lds_dwordx4 v135, s[0:1]
	s_add_u32 m0, s8, 0x4000
	s_nop 0
	global_load_lds_dwordx4 v136, s[6:7]
	s_add_u32 m0, m0, 0x400
	s_nop 0
	global_load_lds_dwordx4 v137, s[6:7]
	s_add_u32 m0, m0, 0x400
	s_nop 0
	global_load_lds_dwordx4 v138, s[6:7]
	s_add_u32 m0, m0, 0x400
	s_nop 0
	global_load_lds_dwordx4 v139, s[6:7]
	s_add_u32 m0, s8, 0x14000
	s_nop 0
	global_load_lds_dwordx4 v140, s[0:1]
	s_add_u32 m0, m0, 0x400
	s_nop 0
	global_load_lds_dwordx4 v141, s[0:1]
	s_add_u32 m0, m0, 0x400
	s_nop 0
	global_load_lds_dwordx4 v142, s[0:1]
	s_add_u32 m0, m0, 0x400
	s_nop 0
	global_load_lds_dwordx4 v143, s[0:1]
.Lff2_d3:
	s_add_u32 s6, s6, 0x80
	s_addc_u32 s7, s7, 0
	s_add_u32 s0, s0, 0x80
	s_addc_u32 s1, s1, 0
	ds_read_b128 v[166:169], v146 offset:32768
	ds_read_b128 v[170:173], v146 offset:34816
	ds_read_b128 v[174:177], v146 offset:36864
	ds_read_b128 v[178:181], v146 offset:38912
	ds_read_b128 v[222:225], v144 offset:32768
	ds_read_b128 v[226:229], v144 offset:34816
	ds_read_b128 v[230:233], v144 offset:36864
	ds_read_b128 v[234:237], v144 offset:38912
	ds_read_b128 v[238:241], v144 offset:40960
	ds_read_b128 v[242:245], v144 offset:43008
	ds_read_b128 v[198:201], v144 offset:45056
	ds_read_b128 v[152:155], v144 offset:47104
	ds_read_b128 v[182:185], v147 offset:32768
	ds_read_b128 v[186:189], v147 offset:34816
	ds_read_b128 v[190:193], v147 offset:36864
	ds_read_b128 v[194:197], v147 offset:38912
	s_waitcnt lgkmcnt(8)
	v_mfma_f32_16x16x32_bf16 v[0:3], v[166:169], v[222:225], v[0:3]
	v_mfma_f32_16x16x32_bf16 v[4:7], v[170:173], v[222:225], v[4:7]
	v_mfma_f32_16x16x32_bf16 v[8:11], v[174:177], v[222:225], v[8:11]
	v_mfma_f32_16x16x32_bf16 v[12:15], v[178:181], v[222:225], v[12:15]
	v_mfma_f32_16x16x32_bf16 v[16:19], v[166:169], v[226:229], v[16:19]
	v_mfma_f32_16x16x32_bf16 v[20:23], v[170:173], v[226:229], v[20:23]
	v_mfma_f32_16x16x32_bf16 v[24:27], v[174:177], v[226:229], v[24:27]
	v_mfma_f32_16x16x32_bf16 v[28:31], v[178:181], v[226:229], v[28:31]
	v_mfma_f32_16x16x32_bf16 v[32:35], v[166:169], v[230:233], v[32:35]
	v_mfma_f32_16x16x32_bf16 v[36:39], v[170:173], v[230:233], v[36:39]
	v_mfma_f32_16x16x32_bf16 v[40:43], v[174:177], v[230:233], v[40:43]
	v_mfma_f32_16x16x32_bf16 v[44:47], v[178:181], v[230:233], v[44:47]
	v_mfma_f32_16x16x32_bf16 v[48:51], v[166:169], v[234:237], v[48:51]
	v_mfma_f32_16x16x32_bf16 v[52:55], v[170:173], v[234:237], v[52:55]
	v_mfma_f32_16x16x32_bf16 v[56:59], v[174:177], v[234:237], v[56:59]
	v_mfma_f32_16x16x32_bf16 v[60:63], v[178:181], v[234:237], v[60:63]
	ds_read_b128 v[222:225], v145 offset:32768
	ds_read_b128 v[226:229], v145 offset:34816
	ds_read_b128 v[230:233], v145 offset:36864
	ds_read_b128 v[234:237], v145 offset:38912
	s_waitcnt lgkmcnt(8)
	v_mfma_f32_16x16x32_bf16 v[64:67], v[166:169], v[238:241], v[64:67]
	v_mfma_f32_16x16x32_bf16 v[68:71], v[170:173], v[238:241], v[68:71]
	v_mfma_f32_16x16x32_bf16 v[72:75], v[174:177], v[238:241], v[72:75]
	v_mfma_f32_16x16x32_bf16 v[76:79], v[178:181], v[238:241], v[76:79]
	v_mfma_f32_16x16x32_bf16 v[80:83], v[166:169], v[242:245], v[80:83]
	v_mfma_f32_16x16x32_bf16 v[84:87], v[170:173], v[242:245], v[84:87]
	v_mfma_f32_16x16x32_bf16 v[88:91], v[174:177], v[242:245], v[88:91]
	v_mfma_f32_16x16x32_bf16 v[92:95], v[178:181], v[242:245], v[92:95]
	v_mfma_f32_16x16x32_bf16 v[96:99], v[166:169], v[198:201], v[96:99]
	v_mfma_f32_16x16x32_bf16 v[100:103], v[170:173], v[198:201], v[100:103]
	v_mfma_f32_16x16x32_bf16 v[104:107], v[174:177], v[198:201], v[104:107]
	v_mfma_f32_16x16x32_bf16 v[108:111], v[178:181], v[198:201], v[108:111]
	v_mfma_f32_16x16x32_bf16 v[112:115], v[166:169], v[152:155], v[112:115]
	v_mfma_f32_16x16x32_bf16 v[116:119], v[170:173], v[152:155], v[116:119]
	v_mfma_f32_16x16x32_bf16 v[120:123], v[174:177], v[152:155], v[120:123]
	v_mfma_f32_16x16x32_bf16 v[124:127], v[178:181], v[152:155], v[124:127]
	ds_read_b128 v[238:241], v145 offset:40960
	ds_read_b128 v[242:245], v145 offset:43008
	ds_read_b128 v[198:201], v145 offset:45056
	ds_read_b128 v[152:155], v145 offset:47104
	s_waitcnt lgkmcnt(4)
	v_mfma_f32_16x16x32_bf16 v[0:3], v[182:185], v[222:225], v[0:3]
	v_mfma_f32_16x16x32_bf16 v[4:7], v[186:189], v[222:225], v[4:7]
	v_mfma_f32_16x16x32_bf16 v[8:11], v[190:193], v[222:225], v[8:11]
	v_mfma_f32_16x16x32_bf16 v[12:15], v[194:197], v[222:225], v[12:15]
	v_mfma_f32_16x16x32_bf16 v[16:19], v[182:185], v[226:229], v[16:19]
	v_mfma_f32_16x16x32_bf16 v[20:23], v[186:189], v[226:229], v[20:23]
	v_mfma_f32_16x16x32_bf16 v[24:27], v[190:193], v[226:229], v[24:27]
	v_mfma_f32_16x16x32_bf16 v[28:31], v[194:197], v[226:229], v[28:31]
	v_mfma_f32_16x16x32_bf16 v[32:35], v[182:185], v[230:233], v[32:35]
	v_mfma_f32_16x16x32_bf16 v[36:39], v[186:189], v[230:233], v[36:39]
	v_mfma_f32_16x16x32_bf16 v[40:43], v[190:193], v[230:233], v[40:43]
	v_mfma_f32_16x16x32_bf16 v[44:47], v[194:197], v[230:233], v[44:47]
	v_mfma_f32_16x16x32_bf16 v[48:51], v[182:185], v[234:237], v[48:51]
	v_mfma_f32_16x16x32_bf16 v[52:55], v[186:189], v[234:237], v[52:55]
	v_mfma_f32_16x16x32_bf16 v[56:59], v[190:193], v[234:237], v[56:59]
	v_mfma_f32_16x16x32_bf16 v[60:63], v[194:197], v[234:237], v[60:63]
	s_waitcnt lgkmcnt(0)
	v_mfma_f32_16x16x32_bf16 v[64:67], v[182:185], v[238:241], v[64:67]
	v_mfma_f32_16x16x32_bf16 v[68:71], v[186:189], v[238:241], v[68:71]
	v_mfma_f32_16x16x32_bf16 v[72:75], v[190:193], v[238:241], v[72:75]
	v_mfma_f32_16x16x32_bf16 v[76:79], v[194:197], v[238:241], v[76:79]
	v_mfma_f32_16x16x32_bf16 v[80:83], v[182:185], v[242:245], v[80:83]
	v_mfma_f32_16x16x32_bf16 v[84:87], v[186:189], v[242:245], v[84:87]
	v_mfma_f32_16x16x32_bf16 v[88:91], v[190:193], v[242:245], v[88:91]
	v_mfma_f32_16x16x32_bf16 v[92:95], v[194:197], v[242:245], v[92:95]
	v_mfma_f32_16x16x32_bf16 v[96:99], v[182:185], v[198:201], v[96:99]
	v_mfma_f32_16x16x32_bf16 v[100:103], v[186:189], v[198:201], v[100:103]
	v_mfma_f32_16x16x32_bf16 v[104:107], v[190:193], v[198:201], v[104:107]
	v_mfma_f32_16x16x32_bf16 v[108:111], v[194:197], v[198:201], v[108:111]
	v_mfma_f32_16x16x32_bf16 v[112:115], v[182:185], v[152:155], v[112:115]
	v_mfma_f32_16x16x32_bf16 v[116:119], v[186:189], v[152:155], v[116:119]
	v_mfma_f32_16x16x32_bf16 v[120:123], v[190:193], v[152:155], v[120:123]
	v_mfma_f32_16x16x32_bf16 v[124:127], v[194:197], v[152:155], v[124:127]
	s_add_i32 s5, s5, 1
	s_waitcnt vmcnt(0)
	s_barrier
	s_branch .Lff2_kloop
; template <class AL, class BL>
; DEV void gemm_ktile(Acc& acc, const char* A, const char* B, int wm, int wn, int lr, int lh, const AL& al, const BL& bl,
;                     int tid, int m0, int n0, int knext, char* nxt, R4& ra, R4& rb) {
;     ...
;   for (int ks = 0; ks < 4; ++ks) {
;     const int cur = ks & 1, nx = cur ^ 1;
;     if (ks < 3) {
; #pragma unroll
;       for (int i = 0; i < 4; ++i) a[nx][i] = *(const bf16x8*)(pa + 32 * i * LDSROW + (ks + 1) * 32);
; #pragma unroll
;       for (int j = 0; j < 2; ++j) b[nx][j] = *(const bf16x8*)(pb + 32 * j * LDSROW + (ks + 1) * 32);
;     }
;     __builtin_amdgcn_sched_barrier(0);
; #pragma unroll
;     for (int i = 0; i < 4; ++i)
; #pragma unroll
;       for (int j = 0; j < 2; ++j)
;         acc[i][j] = __builtin_amdgcn_mfma_f32_32x32x16_bf16(a[cur][i], b[cur][j], acc[i][j], 0, 0, 0);
.Lff2_last:
	ds_read_b128 v[166:169], v146 offset:32768
	ds_read_b128 v[170:173], v146 offset:34816
	ds_read_b128 v[174:177], v146 offset:36864
	ds_read_b128 v[178:181], v146 offset:38912
	ds_read_b128 v[222:225], v144 offset:32768
	ds_read_b128 v[226:229], v144 offset:34816
	ds_read_b128 v[230:233], v144 offset:36864
	ds_read_b128 v[234:237], v144 offset:38912
	ds_read_b128 v[238:241], v144 offset:40960
	ds_read_b128 v[242:245], v144 offset:43008
	ds_read_b128 v[198:201], v144 offset:45056
	ds_read_b128 v[152:155], v144 offset:47104
	ds_read_b128 v[182:185], v147 offset:32768
	ds_read_b128 v[186:189], v147 offset:34816
	ds_read_b128 v[190:193], v147 offset:36864
	ds_read_b128 v[194:197], v147 offset:38912
	s_waitcnt lgkmcnt(8)
	v_mfma_f32_16x16x32_bf16 v[0:3], v[166:169], v[222:225], v[0:3]
	v_mfma_f32_16x16x32_bf16 v[4:7], v[170:173], v[222:225], v[4:7]
	v_mfma_f32_16x16x32_bf16 v[8:11], v[174:177], v[222:225], v[8:11]
	v_mfma_f32_16x16x32_bf16 v[12:15], v[178:181], v[222:225], v[12:15]
	v_mfma_f32_16x16x32_bf16 v[16:19], v[166:169], v[226:229], v[16:19]
	v_mfma_f32_16x16x32_bf16 v[20:23], v[170:173], v[226:229], v[20:23]
	v_mfma_f32_16x16x32_bf16 v[24:27], v[174:177], v[226:229], v[24:27]
	v_mfma_f32_16x16x32_bf16 v[28:31], v[178:181], v[226:229], v[28:31]
	v_mfma_f32_16x16x32_bf16 v[32:35], v[166:169], v[230:233], v[32:35]
	v_mfma_f32_16x16x32_bf16 v[36:39], v[170:173], v[230:233], v[36:39]
	v_mfma_f32_16x16x32_bf16 v[40:43], v[174:177], v[230:233], v[40:43]
	v_mfma_f32_16x16x32_bf16 v[44:47], v[178:181], v[230:233], v[44:47]
	v_mfma_f32_16x16x32_bf16 v[48:51], v[166:169], v[234:237], v[48:51]
	v_mfma_f32_16x16x32_bf16 v[52:55], v[170:173], v[234:237], v[52:55]
	v_mfma_f32_16x16x32_bf16 v[56:59], v[174:177], v[234:237], v[56:59]
	v_mfma_f32_16x16x32_bf16 v[60:63], v[178:181], v[234:237], v[60:63]
	ds_read_b128 v[222:225], v145 offset:32768
	ds_read_b128 v[226:229], v145 offset:34816
	ds_read_b128 v[230:233], v145 offset:36864
	ds_read_b128 v[234:237], v145 offset:38912
	s_waitcnt lgkmcnt(8)
	v_mfma_f32_16x16x32_bf16 v[64:67], v[166:169], v[238:241], v[64:67]
	v_mfma_f32_16x16x32_bf16 v[68:71], v[170:173], v[238:241], v[68:71]
	v_mfma_f32_16x16x32_bf16 v[72:75], v[174:177], v[238:241], v[72:75]
	v_mfma_f32_16x16x32_bf16 v[76:79], v[178:181], v[238:241], v[76:79]
	v_mfma_f32_16x16x32_bf16 v[80:83], v[166:169], v[242:245], v[80:83]
	v_mfma_f32_16x16x32_bf16 v[84:87], v[170:173], v[242:245], v[84:87]
	v_mfma_f32_16x16x32_bf16 v[88:91], v[174:177], v[242:245], v[88:91]
	v_mfma_f32_16x16x32_bf16 v[92:95], v[178:181], v[242:245], v[92:95]
	v_mfma_f32_16x16x32_bf16 v[96:99], v[166:169], v[198:201], v[96:99]
	v_mfma_f32_16x16x32_bf16 v[100:103], v[170:173], v[198:201], v[100:103]
	v_mfma_f32_16x16x32_bf16 v[104:107], v[174:177], v[198:201], v[104:107]
	v_mfma_f32_16x16x32_bf16 v[108:111], v[178:181], v[198:201], v[108:111]
	v_mfma_f32_16x16x32_bf16 v[112:115], v[166:169], v[152:155], v[112:115]
	v_mfma_f32_16x16x32_bf16 v[116:119], v[170:173], v[152:155], v[116:119]
	v_mfma_f32_16x16x32_bf16 v[120:123], v[174:177], v[152:155], v[120:123]
	v_mfma_f32_16x16x32_bf16 v[124:127], v[178:181], v[152:155], v[124:127]
	ds_read_b128 v[238:241], v145 offset:40960
	ds_read_b128 v[242:245], v145 offset:43008
	ds_read_b128 v[198:201], v145 offset:45056
	ds_read_b128 v[152:155], v145 offset:47104
	s_waitcnt lgkmcnt(4)
	v_mfma_f32_16x16x32_bf16 v[0:3], v[182:185], v[222:225], v[0:3]
	v_mfma_f32_16x16x32_bf16 v[4:7], v[186:189], v[222:225], v[4:7]
	v_mfma_f32_16x16x32_bf16 v[8:11], v[190:193], v[222:225], v[8:11]
	v_mfma_f32_16x16x32_bf16 v[12:15], v[194:197], v[222:225], v[12:15]
	v_mfma_f32_16x16x32_bf16 v[16:19], v[182:185], v[226:229], v[16:19]
	v_mfma_f32_16x16x32_bf16 v[20:23], v[186:189], v[226:229], v[20:23]
	v_mfma_f32_16x16x32_bf16 v[24:27], v[190:193], v[226:229], v[24:27]
	v_mfma_f32_16x16x32_bf16 v[28:31], v[194:197], v[226:229], v[28:31]
	v_mfma_f32_16x16x32_bf16 v[32:35], v[182:185], v[230:233], v[32:35]
	v_mfma_f32_16x16x32_bf16 v[36:39], v[186:189], v[230:233], v[36:39]
	v_mfma_f32_16x16x32_bf16 v[40:43], v[190:193], v[230:233], v[40:43]
	v_mfma_f32_16x16x32_bf16 v[44:47], v[194:197], v[230:233], v[44:47]
	v_mfma_f32_16x16x32_bf16 v[48:51], v[182:185], v[234:237], v[48:51]
	v_mfma_f32_16x16x32_bf16 v[52:55], v[186:189], v[234:237], v[52:55]
	v_mfma_f32_16x16x32_bf16 v[56:59], v[190:193], v[234:237], v[56:59]
	v_mfma_f32_16x16x32_bf16 v[60:63], v[194:197], v[234:237], v[60:63]
	s_waitcnt lgkmcnt(0)
	v_mfma_f32_16x16x32_bf16 v[64:67], v[182:185], v[238:241], v[64:67]
	v_mfma_f32_16x16x32_bf16 v[68:71], v[186:189], v[238:241], v[68:71]
	v_mfma_f32_16x16x32_bf16 v[72:75], v[190:193], v[238:241], v[72:75]
	v_mfma_f32_16x16x32_bf16 v[76:79], v[194:197], v[238:241], v[76:79]
	v_mfma_f32_16x16x32_bf16 v[80:83], v[182:185], v[242:245], v[80:83]
	v_mfma_f32_16x16x32_bf16 v[84:87], v[186:189], v[242:245], v[84:87]
	v_mfma_f32_16x16x32_bf16 v[88:91], v[190:193], v[242:245], v[88:91]
	v_mfma_f32_16x16x32_bf16 v[92:95], v[194:197], v[242:245], v[92:95]
	v_mfma_f32_16x16x32_bf16 v[96:99], v[182:185], v[198:201], v[96:99]
	v_mfma_f32_16x16x32_bf16 v[100:103], v[186:189], v[198:201], v[100:103]
	v_mfma_f32_16x16x32_bf16 v[104:107], v[190:193], v[198:201], v[104:107]
	v_mfma_f32_16x16x32_bf16 v[108:111], v[194:197], v[198:201], v[108:111]
	v_mfma_f32_16x16x32_bf16 v[112:115], v[182:185], v[152:155], v[112:115]
	v_mfma_f32_16x16x32_bf16 v[116:119], v[186:189], v[152:155], v[116:119]
	v_mfma_f32_16x16x32_bf16 v[120:123], v[190:193], v[152:155], v[120:123]
	v_mfma_f32_16x16x32_bf16 v[124:127], v[194:197], v[152:155], v[124:127]
	s_barrier
; template <class F>
; DEV void acc_foreach(Acc& acc, int m0, int n0, F f) {
;   asm volatile("s_nop 7\n\ts_nop 7\n\ts_nop 3" ::: "memory");
;   const int tid = tidx_full();
;   const int wave = tid >> 6, lane = tid & 63;
;   const int wm = (wave >> 2) * 128, wn = (wave & 3) * 64;
;   const int lr = lane & 31, lh = lane >> 5;
; #pragma unroll
;   for (int i = 0; i < 4; ++i)
; #pragma unroll
;     for (int j = 0; j < 2; ++j)
; #pragma unroll
;       for (int r = 0; r < 16; ++r) {
;         const int m = m0 + wm + 32 * i + (r & 3) + 8 * (r >> 2) + 4 * lh;
;         const int n = n0 + wn + 32 * j + lr;
;         float v = acc[i][j][r];
;         f(m, n, v);
;         acc[i][j][r] = v;
;       }
; DEV void phase_ff2(const Params& p, int g, char* smem) {
;     ...
;     const float* gt = mod + (size_t)(bg0 + m0 / L) * DIN + 5120;
;     acc_foreach(acc, m0, n0, [&](int m, int n, float& v) { X1[(size_t)m * D + n] += gt[n] * v; });
	v_mov_b32_e32 v207, 0x25810
	v_mov_b32_e32 v208, 0x2000
	v_mov_b32_e32 v209, 0x3000
	v_mov_b32_e32 v210, 0x1000
	s_abs_i32 s1, s3
	v_readlane_b32 s5, v252, 17
	s_mul_hi_u32 s5, s1, s5
	v_readlane_b32 s8, v252, 16
	s_mul_i32 s6, s5, s8
	s_sub_i32 s1, s1, s6
	s_ashr_i32 s0, s3, 31
	s_add_i32 s6, s5, 1
	s_sub_i32 s7, s1, s8
	s_cmp_ge_u32 s1, s8
	s_cselect_b32 s5, s6, s5
	s_cselect_b32 s1, s7, s1
	s_add_i32 s6, s5, 1
	s_cmp_ge_u32 s1, s8
	s_cselect_b32 s1, s6, s5
	s_xor_b32 s1, s1, s0
	s_sub_i32 s0, s1, s0
	s_add_i32 s0, s0, s16
	s_mul_hi_i32 s1, s0, 0x6000
	s_mulk_i32 s0, 0x6000
	s_add_u32 s0, s88, s0
	s_addc_u32 s1, s89, s1
	s_add_u32 s0, s0, 0x2005000
	s_addc_u32 s1, s1, 0
	s_waitcnt vmcnt(0)
	s_nop 7
	s_nop 7
	s_nop 3
	v_and_b32_e32 v160, 63, v202
	v_lshrrev_b32_e32 v161, 6, v202
	v_and_b32_e32 v164, 3, v161
	v_lshlrev_b32_e32 v164, 13, v164
	v_add_u32_e32 v164, 0x8000, v164
	v_lshrrev_b32_e32 v160, 2, v161
	v_lshl_add_u32 v164, v160, 16, v164
	v_and_b32_e32 v160, 63, v202
	v_lshrrev_b32_e32 v166, 4, v160
	v_and_b32_e32 v167, 15, v160
	v_lshrrev_b32_e32 v182, 2, v161
	v_lshl_add_u32 v182, v182, 7, v166
	v_add_u32_e32 v182, s3, v182
	v_lshlrev_b32_e32 v182, 12, v182
	v_and_b32_e32 v184, 3, v161
	v_lshl_add_u32 v184, v184, 4, v167
	v_lshlrev_b32_e32 v184, 4, v184
	s_lshl_b32 s100, s2, 2
	v_add_u32_e32 v184, s100, v184
	v_add_u32_e32 v182, v182, v184
	v_mov_b32_e32 v183, v182
	global_load_dwordx4 v[128:131], v182, s[64:65]
	v_add_u32_e32 v182, 0x4000, v182
	global_load_dwordx4 v[132:135], v182, s[64:65]
	v_add_u32_e32 v182, 0x4000, v182
	global_load_dwordx4 v[136:139], v182, s[64:65]
	v_add_u32_e32 v182, 0x4000, v182
	global_load_dwordx4 v[140:143], v182, s[64:65]
	v_add_u32_e32 v182, 0x4000, v182
	global_load_dwordx4 v[144:147], v182, s[64:65]
	v_add_u32_e32 v182, 0x4000, v182
	global_load_dwordx4 v[148:151], v182, s[64:65]
	v_add_u32_e32 v182, 0x4000, v182
	global_load_dwordx4 v[152:155], v182, s[64:65]
	v_add_u32_e32 v182, 0x4000, v182
	global_load_dwordx4 v[156:159], v182, s[64:65]
	v_add_u32_e32 v182, 0x4000, v182
	global_load_dwordx4 v[188:191], v182, s[64:65]
	v_add_u32_e32 v182, 0x4000, v182
	global_load_dwordx4 v[192:195], v182, s[64:65]
	v_add_u32_e32 v182, 0x4000, v182
	global_load_dwordx4 v[196:199], v182, s[64:65]
	v_add_u32_e32 v182, 0x4000, v182
	global_load_dwordx4 v[222:225], v182, s[64:65]
	v_add_u32_e32 v182, 0x4000, v182
	global_load_dwordx4 v[226:229], v182, s[64:65]
	v_add_u32_e32 v182, 0x4000, v182
	global_load_dwordx4 v[230:233], v182, s[64:65]
	v_add_u32_e32 v182, 0x4000, v182
	global_load_dwordx4 v[234:237], v182, s[64:65]
	v_add_u32_e32 v182, 0x4000, v182
	global_load_dwordx4 v[238:241], v182, s[64:65]
	v_add_u32_e32 v182, 0x4000, v182
	global_load_dwordx4 v[168:171], v184, s[0:1]
	v_and_b32_e32 v166, 15, v160
	v_lshrrev_b32_e32 v167, 4, v160
	v_lshl_add_u32 v180, v166, 8, v164
	v_and_b32_e32 v166, 7, v166
	v_xor_b32_e32 v166, v166, v167
	v_lshlrev_b32_e32 v166, 4, v166
	v_add_u32_e32 v172, v180, v166
	v_xor_b32_e32 v167, 0x40, v166
	v_add_u32_e32 v173, v180, v167
	v_xor_b32_e32 v167, 0x80, v166
	v_add_u32_e32 v174, v180, v167
	v_xor_b32_e32 v167, 0xc0, v166
	v_add_u32_e32 v175, v180, v167
	v_lshrrev_b32_e32 v166, 4, v160
	v_and_b32_e32 v167, 15, v160
	v_xor_b32_e32 v167, v166, v167
	v_lshlrev_b32_e32 v167, 4, v167
	v_lshl_add_u32 v180, v166, 8, v164
	v_add_u32_e32 v181, v180, v167
	v_xor_b32_e32 v167, 0x40, v167
	v_add_u32_e32 v166, v180, v167
	v_mov_b32_e32 v180, v181
	v_mov_b32_e32 v181, v166
	ds_write_b128 v172, v[0:3]
	ds_write_b128 v173, v[4:7]
	ds_write_b128 v174, v[8:11]
	ds_write_b128 v175, v[12:15]
	ds_write_b128 v172, v[16:19] offset:4096
	ds_write_b128 v173, v[20:23] offset:4096
	ds_write_b128 v174, v[24:27] offset:4096
	ds_write_b128 v175, v[28:31] offset:4096
	s_waitcnt lgkmcnt(0)
	ds_read_b128 v[0:3], v180
	ds_read_b128 v[4:7], v181 offset:1024
	ds_read_b128 v[8:11], v180 offset:2048
	ds_read_b128 v[12:15], v181 offset:3072
	ds_read_b128 v[16:19], v180 offset:4096
	ds_read_b128 v[20:23], v181 offset:5120
	ds_read_b128 v[24:27], v180 offset:6144
	ds_read_b128 v[28:31], v181 offset:7168
	s_waitcnt vmcnt(0)
	s_waitcnt lgkmcnt(7)
	v_fma_f32 v0, v168, v0, v128
	v_fma_f32 v1, v169, v1, v129
	v_fma_f32 v2, v170, v2, v130
	v_fma_f32 v3, v171, v3, v131
	global_store_dwordx4 v183, v[0:3], s[64:65]
	v_add_u32_e32 v183, 0x4000, v183
	s_waitcnt lgkmcnt(6)
	v_fma_f32 v4, v168, v4, v132
	v_fma_f32 v5, v169, v5, v133
	v_fma_f32 v6, v170, v6, v134
	v_fma_f32 v7, v171, v7, v135
	global_store_dwordx4 v183, v[4:7], s[64:65]
	v_add_u32_e32 v183, 0x4000, v183
	s_waitcnt lgkmcnt(5)
	v_fma_f32 v8, v168, v8, v136
	v_fma_f32 v9, v169, v9, v137
	v_fma_f32 v10, v170, v10, v138
	v_fma_f32 v11, v171, v11, v139
	global_store_dwordx4 v183, v[8:11], s[64:65]
	v_add_u32_e32 v183, 0x4000, v183
	s_waitcnt lgkmcnt(4)
	v_fma_f32 v12, v168, v12, v140
	v_fma_f32 v13, v169, v13, v141
	v_fma_f32 v14, v170, v14, v142
	v_fma_f32 v15, v171, v15, v143
	global_store_dwordx4 v183, v[12:15], s[64:65]
	v_add_u32_e32 v183, 0x4000, v183
	s_waitcnt lgkmcnt(3)
	v_fma_f32 v16, v168, v16, v144
	v_fma_f32 v17, v169, v17, v145
	v_fma_f32 v18, v170, v18, v146
	v_fma_f32 v19, v171, v19, v147
	global_store_dwordx4 v183, v[16:19], s[64:65]
	v_add_u32_e32 v183, 0x4000, v183
	s_waitcnt lgkmcnt(2)
	v_fma_f32 v20, v168, v20, v148
	v_fma_f32 v21, v169, v21, v149
	v_fma_f32 v22, v170, v22, v150
	v_fma_f32 v23, v171, v23, v151
	global_store_dwordx4 v183, v[20:23], s[64:65]
	v_add_u32_e32 v183, 0x4000, v183
	s_waitcnt lgkmcnt(1)
	v_fma_f32 v24, v168, v24, v152
	v_fma_f32 v25, v169, v25, v153
	v_fma_f32 v26, v170, v26, v154
	v_fma_f32 v27, v171, v27, v155
	global_store_dwordx4 v183, v[24:27], s[64:65]
	v_add_u32_e32 v183, 0x4000, v183
	s_waitcnt lgkmcnt(0)
; template <class F>
; DEV void acc_foreach(Acc& acc, int m0, int n0, F f) {
;     ...
; #pragma unroll
;   for (int i = 0; i < 4; ++i)
; #pragma unroll
;     for (int j = 0; j < 2; ++j)
; #pragma unroll
;       for (int r = 0; r < 16; ++r) {
;         const int m = m0 + wm + 32 * i + (r & 3) + 8 * (r >> 2) + 4 * lh;
;         const int n = n0 + wn + 32 * j + lr;
;         float v = acc[i][j][r];
;         f(m, n, v);
;         acc[i][j][r] = v;
;       }
; DEV void phase_ff2(const Params& p, int g, char* smem) {
;     ...
;     const float* gt = mod + (size_t)(bg0 + m0 / L) * DIN + 5120;
;     acc_foreach(acc, m0, n0, [&](int m, int n, float& v) { X1[(size_t)m * D + n] += gt[n] * v; });
	v_fma_f32 v28, v168, v28, v156
	v_fma_f32 v29, v169, v29, v157
	v_fma_f32 v30, v170, v30, v158
	v_fma_f32 v31, v171, v31, v159
	global_store_dwordx4 v183, v[28:31], s[64:65]
	v_add_u32_e32 v183, 0x4000, v183
	global_load_dwordx4 v[128:131], v182, s[64:65]
	v_add_u32_e32 v182, 0x4000, v182
	global_load_dwordx4 v[132:135], v182, s[64:65]
	v_add_u32_e32 v182, 0x4000, v182
	global_load_dwordx4 v[136:139], v182, s[64:65]
	v_add_u32_e32 v182, 0x4000, v182
	global_load_dwordx4 v[140:143], v182, s[64:65]
	v_add_u32_e32 v182, 0x4000, v182
	global_load_dwordx4 v[144:147], v182, s[64:65]
	v_add_u32_e32 v182, 0x4000, v182
	global_load_dwordx4 v[148:151], v182, s[64:65]
	v_add_u32_e32 v182, 0x4000, v182
	global_load_dwordx4 v[152:155], v182, s[64:65]
	v_add_u32_e32 v182, 0x4000, v182
	global_load_dwordx4 v[156:159], v182, s[64:65]
	v_add_u32_e32 v182, 0x4000, v182
	ds_write_b128 v172, v[32:35]
	ds_write_b128 v173, v[36:39]
	ds_write_b128 v174, v[40:43]
	ds_write_b128 v175, v[44:47]
	ds_write_b128 v172, v[48:51] offset:4096
	ds_write_b128 v173, v[52:55] offset:4096
	ds_write_b128 v174, v[56:59] offset:4096
	ds_write_b128 v175, v[60:63] offset:4096
	s_waitcnt lgkmcnt(0)
	ds_read_b128 v[32:35], v180
	ds_read_b128 v[36:39], v181 offset:1024
	ds_read_b128 v[40:43], v180 offset:2048
	ds_read_b128 v[44:47], v181 offset:3072
	ds_read_b128 v[48:51], v180 offset:4096
	ds_read_b128 v[52:55], v181 offset:5120
	ds_read_b128 v[56:59], v180 offset:6144
	ds_read_b128 v[60:63], v181 offset:7168
	s_waitcnt lgkmcnt(7)
	v_fma_f32 v32, v168, v32, v188
	v_fma_f32 v33, v169, v33, v189
	v_fma_f32 v34, v170, v34, v190
	v_fma_f32 v35, v171, v35, v191
	global_store_dwordx4 v183, v[32:35], s[64:65]
	v_add_u32_e32 v183, 0x4000, v183
	s_waitcnt lgkmcnt(6)
	v_fma_f32 v36, v168, v36, v192
	v_fma_f32 v37, v169, v37, v193
	v_fma_f32 v38, v170, v38, v194
	v_fma_f32 v39, v171, v39, v195
	global_store_dwordx4 v183, v[36:39], s[64:65]
	v_add_u32_e32 v183, 0x4000, v183
	s_waitcnt lgkmcnt(5)
	v_fma_f32 v40, v168, v40, v196
	v_fma_f32 v41, v169, v41, v197
	v_fma_f32 v42, v170, v42, v198
	v_fma_f32 v43, v171, v43, v199
	global_store_dwordx4 v183, v[40:43], s[64:65]
	v_add_u32_e32 v183, 0x4000, v183
	s_waitcnt lgkmcnt(4)
	v_fma_f32 v44, v168, v44, v222
	v_fma_f32 v45, v169, v45, v223
	v_fma_f32 v46, v170, v46, v224
	v_fma_f32 v47, v171, v47, v225
	global_store_dwordx4 v183, v[44:47], s[64:65]
	v_add_u32_e32 v183, 0x4000, v183
	s_waitcnt lgkmcnt(3)
	v_fma_f32 v48, v168, v48, v226
	v_fma_f32 v49, v169, v49, v227
	v_fma_f32 v50, v170, v50, v228
	v_fma_f32 v51, v171, v51, v229
	global_store_dwordx4 v183, v[48:51], s[64:65]
	v_add_u32_e32 v183, 0x4000, v183
	s_waitcnt lgkmcnt(2)
	v_fma_f32 v52, v168, v52, v230
	v_fma_f32 v53, v169, v53, v231
	v_fma_f32 v54, v170, v54, v232
	v_fma_f32 v55, v171, v55, v233
	global_store_dwordx4 v183, v[52:55], s[64:65]
	v_add_u32_e32 v183, 0x4000, v183
	s_waitcnt lgkmcnt(1)
	v_fma_f32 v56, v168, v56, v234
	v_fma_f32 v57, v169, v57, v235
	v_fma_f32 v58, v170, v58, v236
	v_fma_f32 v59, v171, v59, v237
	global_store_dwordx4 v183, v[56:59], s[64:65]
	v_add_u32_e32 v183, 0x4000, v183
	s_waitcnt lgkmcnt(0)
	v_fma_f32 v60, v168, v60, v238
	v_fma_f32 v61, v169, v61, v239
	v_fma_f32 v62, v170, v62, v240
	v_fma_f32 v63, v171, v63, v241
	global_store_dwordx4 v183, v[60:63], s[64:65]
	v_add_u32_e32 v183, 0x4000, v183
	global_load_dwordx4 v[188:191], v182, s[64:65]
	v_add_u32_e32 v182, 0x4000, v182
	global_load_dwordx4 v[192:195], v182, s[64:65]
	v_add_u32_e32 v182, 0x4000, v182
	global_load_dwordx4 v[196:199], v182, s[64:65]
	v_add_u32_e32 v182, 0x4000, v182
	global_load_dwordx4 v[222:225], v182, s[64:65]
	v_add_u32_e32 v182, 0x4000, v182
	global_load_dwordx4 v[226:229], v182, s[64:65]
	v_add_u32_e32 v182, 0x4000, v182
	global_load_dwordx4 v[230:233], v182, s[64:65]
	v_add_u32_e32 v182, 0x4000, v182
	global_load_dwordx4 v[234:237], v182, s[64:65]
	v_add_u32_e32 v182, 0x4000, v182
	global_load_dwordx4 v[238:241], v182, s[64:65]
	v_add_u32_e32 v182, 0x4000, v182
	ds_write_b128 v172, v[64:67]
	ds_write_b128 v173, v[68:71]
	ds_write_b128 v174, v[72:75]
	ds_write_b128 v175, v[76:79]
	ds_write_b128 v172, v[80:83] offset:4096
	ds_write_b128 v173, v[84:87] offset:4096
	ds_write_b128 v174, v[88:91] offset:4096
	ds_write_b128 v175, v[92:95] offset:4096
	s_waitcnt lgkmcnt(0)
	ds_read_b128 v[64:67], v180
	ds_read_b128 v[68:71], v181 offset:1024
	ds_read_b128 v[72:75], v180 offset:2048
	ds_read_b128 v[76:79], v181 offset:3072
	ds_read_b128 v[80:83], v180 offset:4096
	ds_read_b128 v[84:87], v181 offset:5120
	ds_read_b128 v[88:91], v180 offset:6144
	ds_read_b128 v[92:95], v181 offset:7168
	s_waitcnt vmcnt(16)
; template <class F>
; DEV void acc_foreach(Acc& acc, int m0, int n0, F f) {
;   asm volatile("s_nop 7\n\ts_nop 7\n\ts_nop 3" ::: "memory");
;   const int tid = tidx_full();
;   const int wave = tid >> 6, lane = tid & 63;
;   const int wm = (wave >> 2) * 128, wn = (wave & 3) * 64;
;   const int lr = lane & 31, lh = lane >> 5;
; #pragma unroll
;   for (int i = 0; i < 4; ++i)
; #pragma unroll
;     for (int j = 0; j < 2; ++j)
; #pragma unroll
;       for (int r = 0; r < 16; ++r) {
;         const int m = m0 + wm + 32 * i + (r & 3) + 8 * (r >> 2) + 4 * lh;
;         const int n = n0 + wn + 32 * j + lr;
;         float v = acc[i][j][r];
;         f(m, n, v);
;         acc[i][j][r] = v;
;       }
; DEV void phase_ff2(const Params& p, int g, char* smem) {
;     ...
;   for (int iter = 0;; ++iter) {
;     int mt, nt;
;     if (!tile_map(iter, 128, 4, mt, nt)) break;
;     const int m0 = mt * 256, n0 = nt * 256;
;     Acc acc;
;     acc_zero(acc);
;     RowLoader al{AB, 4096}, bl{W, 4096};
;     gemm_mainloop(acc, al, bl, m0, n0, 0, 4096, smem);
;     const float* gt = mod + (size_t)(bg0 + m0 / L) * DIN + 5120;
;     acc_foreach(acc, m0, n0, [&](int m, int n, float& v) { X1[(size_t)m * D + n] += gt[n] * v; });
	s_waitcnt lgkmcnt(7)
	v_fma_f32 v64, v168, v64, v128
	v_fma_f32 v65, v169, v65, v129
	v_fma_f32 v66, v170, v66, v130
	v_fma_f32 v67, v171, v67, v131
	global_store_dwordx4 v183, v[64:67], s[64:65]
	v_add_u32_e32 v183, 0x4000, v183
	s_waitcnt lgkmcnt(6)
	v_fma_f32 v68, v168, v68, v132
	v_fma_f32 v69, v169, v69, v133
	v_fma_f32 v70, v170, v70, v134
	v_fma_f32 v71, v171, v71, v135
	global_store_dwordx4 v183, v[68:71], s[64:65]
	v_add_u32_e32 v183, 0x4000, v183
	s_waitcnt lgkmcnt(5)
	v_fma_f32 v72, v168, v72, v136
	v_fma_f32 v73, v169, v73, v137
	v_fma_f32 v74, v170, v74, v138
	v_fma_f32 v75, v171, v75, v139
	global_store_dwordx4 v183, v[72:75], s[64:65]
	v_add_u32_e32 v183, 0x4000, v183
	s_waitcnt lgkmcnt(4)
	v_fma_f32 v76, v168, v76, v140
	v_fma_f32 v77, v169, v77, v141
	v_fma_f32 v78, v170, v78, v142
	v_fma_f32 v79, v171, v79, v143
	global_store_dwordx4 v183, v[76:79], s[64:65]
	v_add_u32_e32 v183, 0x4000, v183
	s_waitcnt lgkmcnt(3)
	v_fma_f32 v80, v168, v80, v144
	v_fma_f32 v81, v169, v81, v145
	v_fma_f32 v82, v170, v82, v146
	v_fma_f32 v83, v171, v83, v147
	global_store_dwordx4 v183, v[80:83], s[64:65]
	v_add_u32_e32 v183, 0x4000, v183
	s_waitcnt lgkmcnt(2)
	v_fma_f32 v84, v168, v84, v148
	v_fma_f32 v85, v169, v85, v149
	v_fma_f32 v86, v170, v86, v150
	v_fma_f32 v87, v171, v87, v151
	global_store_dwordx4 v183, v[84:87], s[64:65]
	v_add_u32_e32 v183, 0x4000, v183
	s_waitcnt lgkmcnt(1)
	v_fma_f32 v88, v168, v88, v152
	v_fma_f32 v89, v169, v89, v153
	v_fma_f32 v90, v170, v90, v154
	v_fma_f32 v91, v171, v91, v155
	global_store_dwordx4 v183, v[88:91], s[64:65]
	v_add_u32_e32 v183, 0x4000, v183
	s_waitcnt lgkmcnt(0)
	v_fma_f32 v92, v168, v92, v156
	v_fma_f32 v93, v169, v93, v157
	v_fma_f32 v94, v170, v94, v158
	v_fma_f32 v95, v171, v95, v159
	global_store_dwordx4 v183, v[92:95], s[64:65]
	v_add_u32_e32 v183, 0x4000, v183
	ds_write_b128 v172, v[96:99]
	ds_write_b128 v173, v[100:103]
	ds_write_b128 v174, v[104:107]
	ds_write_b128 v175, v[108:111]
	ds_write_b128 v172, v[112:115] offset:4096
	ds_write_b128 v173, v[116:119] offset:4096
	ds_write_b128 v174, v[120:123] offset:4096
	ds_write_b128 v175, v[124:127] offset:4096
	s_waitcnt lgkmcnt(0)
	ds_read_b128 v[96:99], v180
	ds_read_b128 v[100:103], v181 offset:1024
	ds_read_b128 v[104:107], v180 offset:2048
	ds_read_b128 v[108:111], v181 offset:3072
	ds_read_b128 v[112:115], v180 offset:4096
	ds_read_b128 v[116:119], v181 offset:5120
	ds_read_b128 v[120:123], v180 offset:6144
	ds_read_b128 v[124:127], v181 offset:7168
	s_waitcnt vmcnt(8)
	s_waitcnt lgkmcnt(7)
	v_fma_f32 v96, v168, v96, v188
	v_fma_f32 v97, v169, v97, v189
	v_fma_f32 v98, v170, v98, v190
	v_fma_f32 v99, v171, v99, v191
	global_store_dwordx4 v183, v[96:99], s[64:65]
	v_add_u32_e32 v183, 0x4000, v183
	s_waitcnt lgkmcnt(6)
	v_fma_f32 v100, v168, v100, v192
	v_fma_f32 v101, v169, v101, v193
	v_fma_f32 v102, v170, v102, v194
	v_fma_f32 v103, v171, v103, v195
	global_store_dwordx4 v183, v[100:103], s[64:65]
	v_add_u32_e32 v183, 0x4000, v183
	s_waitcnt lgkmcnt(5)
	v_fma_f32 v104, v168, v104, v196
	v_fma_f32 v105, v169, v105, v197
	v_fma_f32 v106, v170, v106, v198
	v_fma_f32 v107, v171, v107, v199
	global_store_dwordx4 v183, v[104:107], s[64:65]
	v_add_u32_e32 v183, 0x4000, v183
	s_waitcnt lgkmcnt(4)
	v_fma_f32 v108, v168, v108, v222
	v_fma_f32 v109, v169, v109, v223
	v_fma_f32 v110, v170, v110, v224
	v_fma_f32 v111, v171, v111, v225
	global_store_dwordx4 v183, v[108:111], s[64:65]
	v_add_u32_e32 v183, 0x4000, v183
	s_waitcnt lgkmcnt(3)
	v_fma_f32 v112, v168, v112, v226
	v_fma_f32 v113, v169, v113, v227
	v_fma_f32 v114, v170, v114, v228
	v_fma_f32 v115, v171, v115, v229
	global_store_dwordx4 v183, v[112:115], s[64:65]
	v_add_u32_e32 v183, 0x4000, v183
	s_waitcnt lgkmcnt(2)
	v_fma_f32 v116, v168, v116, v230
	v_fma_f32 v117, v169, v117, v231
	v_fma_f32 v118, v170, v118, v232
	v_fma_f32 v119, v171, v119, v233
	global_store_dwordx4 v183, v[116:119], s[64:65]
	v_add_u32_e32 v183, 0x4000, v183
	s_waitcnt lgkmcnt(1)
	v_fma_f32 v120, v168, v120, v234
	v_fma_f32 v121, v169, v121, v235
	v_fma_f32 v122, v170, v122, v236
	v_fma_f32 v123, v171, v123, v237
	global_store_dwordx4 v183, v[120:123], s[64:65]
	v_add_u32_e32 v183, 0x4000, v183
	s_waitcnt lgkmcnt(0)
	v_fma_f32 v124, v168, v124, v238
	v_fma_f32 v125, v169, v125, v239
	v_fma_f32 v126, v170, v126, v240
	v_fma_f32 v127, v171, v127, v241
	global_store_dwordx4 v183, v[124:127], s[64:65]
	v_add_u32_e32 v183, 0x4000, v183
	s_add_i32 s4, s4, 1
	s_mov_b64 s[2:3], 0
	s_branch .LBB0_1182
